# adds: serialized ds_bpermute butterfly sum reductions (head RMSNorm epilogues, MLA tiles, norm phases) replaced by DPP quad_perm/row_mirror adds and permlane16/32 swaps, same association
# speedup vs baseline: 1.0058x; 1.0058x over previous
.LBB0_44:
	v_add_u32_e32 v21, 0xfffff000, v20
	v_ashrrev_i32_e32 v21, 11, v21
	v_add_u32_e32 v21, 1, v21
	v_cmp_lt_i32_e32 vcc, s76, v20
	v_mov_b64_e32 v[34:35], s[18:19]
	v_add_u32_e32 v20, s4, v20
	v_cndmask_b32_e32 v32, 0, v21, vcc
	v_ashrrev_i32_e32 v33, 31, v32
	v_lshl_add_u64 v[32:33], v[32:33], 0, s[6:7]
	v_mad_u64_u32 v[48:49], s[14:15], v32, s80, v[34:35]
	v_mad_i32_i24 v49, v33, s80, v49
	global_load_dwordx4 v[32:35], v[22:23], off offset:-2048
	global_load_dwordx4 v[36:39], v[22:23], off offset:-1024
	global_load_dwordx4 v[40:43], v[22:23], off
	global_load_dwordx4 v[44:47], v[22:23], off offset:1024
	v_lshl_add_u64 v[52:53], v[48:49], 0, v[2:3]
	v_add_co_u32_e32 v48, vcc, s77, v52
	s_mov_b64 s[14:15], 0x4000
	s_nop 0
	v_addc_co_u32_e32 v49, vcc, 0, v53, vcc
	global_load_dwordx4 v[48:51], v[48:49], off
	s_waitcnt vmcnt(22)
	v_lshl_add_u64 v[72:73], v[52:53], 0, s[14:15]
	s_mov_b64 s[14:15], 0x3000
	s_waitcnt vmcnt(20)
	v_lshl_add_u64 v[76:77], v[52:53], 0, s[14:15]
	v_add_co_u32_e32 v52, vcc, s16, v52
	v_lshl_add_u64 v[22:23], v[22:23], 0, s[8:9]
	s_nop 0
	v_addc_co_u32_e32 v53, vcc, 0, v53, vcc
	global_load_dwordx4 v[52:55], v[52:53], off
	s_nop 0
	global_load_dwordx4 v[56:59], v[72:73], off offset:1024
	global_load_dwordx4 v[60:63], v[76:77], off offset:1024
	global_load_dwordx4 v[64:67], v[72:73], off offset:2048
	global_load_dwordx4 v[68:71], v[76:77], off offset:2048
	s_nop 0
	global_load_dwordx4 v[72:75], v[72:73], off offset:3072
	s_nop 0
	global_load_dwordx4 v[76:79], v[76:77], off offset:3072
	s_waitcnt vmcnt(11)
	v_mov_b32_e32 v82, v33
	s_waitcnt vmcnt(10)
	v_mov_b32_e32 v83, v37
	v_mov_b32_e32 v80, v32
	v_mov_b32_e32 v81, v36
	v_pk_mul_f32 v[82:83], v[82:83], v[82:83]
	s_waitcnt vmcnt(9)
	v_mov_b32_e32 v84, v41
	v_pk_fma_f32 v[80:81], v[80:81], v[80:81], v[82:83]
	v_mov_b32_e32 v82, v34
	v_mov_b32_e32 v83, v38
	v_pk_fma_f32 v[80:81], v[82:83], v[82:83], v[80:81]
	v_mov_b32_e32 v82, v35
	v_mov_b32_e32 v83, v39
	s_waitcnt vmcnt(8)
	v_mov_b32_e32 v85, v45
	v_pk_fma_f32 v[80:81], v[82:83], v[82:83], v[80:81]
	v_mov_b32_e32 v82, v40
	v_mov_b32_e32 v83, v44
	v_pk_mul_f32 v[84:85], v[84:85], v[84:85]
	v_add_f32_e32 v21, v80, v81
	v_pk_fma_f32 v[82:83], v[82:83], v[82:83], v[84:85]
	v_mov_b32_e32 v84, v42
	v_mov_b32_e32 v85, v46
	v_pk_fma_f32 v[82:83], v[84:85], v[84:85], v[82:83]
	v_mov_b32_e32 v84, v43
	v_mov_b32_e32 v85, v47
	v_pk_fma_f32 v[82:83], v[84:85], v[84:85], v[82:83]
	s_waitcnt vmcnt(7)
	v_pk_add_f32 v[48:49], v[48:49], 1.0 op_sel_hi:[1,0]
	v_add_f32_e32 v21, v21, v82
	v_add_f32_e32 v21, v21, v83
	s_nop 1
	v_pk_mul_f32 v[48:49], v[16:17], v[48:49]
	s_waitcnt lgkmcnt(0)
	v_add_f32_dpp v21, v21, v21 quad_perm:[1,0,3,2] row_mask:0xf bank_mask:0xf
	s_nop 1
	s_waitcnt lgkmcnt(0)
	v_add_f32_dpp v21, v21, v21 quad_perm:[2,3,0,1] row_mask:0xf bank_mask:0xf
	s_nop 1
	s_waitcnt lgkmcnt(0)
	v_add_f32_dpp v21, v21, v21 row_half_mirror row_mask:0xf bank_mask:0xf
	s_nop 1
	s_waitcnt lgkmcnt(0)
	v_add_f32_dpp v21, v21, v21 row_mirror row_mask:0xf bank_mask:0xf
	v_mov_b32_e32 v80, v21
	s_nop 1
	v_permlane16_swap_b32_e32 v80, v21
	s_waitcnt lgkmcnt(0)
	v_add_f32_e32 v21, v21, v80
	v_mov_b32_e32 v80, v21
	s_nop 1
	v_permlane32_swap_b32_e32 v80, v21
	s_waitcnt lgkmcnt(0)
	v_add_f32_e32 v21, v21, v80
	v_fmamk_f32 v21, v21, 0x3a800000, v1
	v_cmp_gt_f32_e32 vcc, s17, v21
	v_mul_f32_e32 v80, 0x4b800000, v21
	s_nop 0
	v_cndmask_b32_e32 v21, v21, v80, vcc
	v_rsq_f32_e32 v21, v21
	s_nop 0
	v_mul_f32_e32 v80, 0x45800000, v21
	v_cndmask_b32_e32 v80, v21, v80, vcc
	v_pk_mul_f32 v[32:33], v[32:33], v[80:81] op_sel_hi:[1,0]
	v_pk_mul_f32 v[34:35], v[34:35], v[80:81] op_sel_hi:[1,0]
	s_waitcnt vmcnt(6)
	v_pk_fma_f32 v[32:33], v[48:49], v[32:33], v[52:53]
	v_pk_add_f32 v[48:49], v[50:51], 1.0 op_sel_hi:[1,0]
	v_cvt_pk_bf16_f32 v32, v32, v33
	v_pk_mul_f32 v[48:49], v[18:19], v[48:49]
	v_cmp_lt_i32_e32 vcc, s36, v20
	v_pk_fma_f32 v[34:35], v[48:49], v[34:35], v[54:55]
	s_or_b64 s[12:13], vcc, s[12:13]
	v_cvt_pk_bf16_f32 v33, v34, v35
	s_waitcnt vmcnt(5)
	v_pk_add_f32 v[34:35], v[56:57], 1.0 op_sel_hi:[1,0]
	global_store_dwordx2 v[24:25], v[32:33], off offset:-1024
	v_pk_mul_f32 v[32:33], v[36:37], v[80:81] op_sel_hi:[1,0]
	v_pk_mul_f32 v[34:35], v[12:13], v[34:35]
	v_pk_add_f32 v[36:37], v[58:59], 1.0 op_sel_hi:[1,0]
	s_waitcnt vmcnt(5)
	v_pk_fma_f32 v[32:33], v[34:35], v[32:33], v[60:61]
	v_pk_mul_f32 v[34:35], v[38:39], v[80:81] op_sel_hi:[1,0]
	v_pk_mul_f32 v[36:37], v[14:15], v[36:37]
	v_cvt_pk_bf16_f32 v32, v32, v33
	v_pk_fma_f32 v[34:35], v[36:37], v[34:35], v[62:63]
	s_waitcnt vmcnt(4)
	v_pk_add_f32 v[36:37], v[66:67], 1.0 op_sel_hi:[1,0]
	v_cvt_pk_bf16_f32 v33, v34, v35
	v_pk_add_f32 v[34:35], v[64:65], 1.0 op_sel_hi:[1,0]
	global_store_dwordx2 v[24:25], v[32:33], off offset:-512
	v_pk_mul_f32 v[32:33], v[40:41], v[80:81] op_sel_hi:[1,0]
	v_pk_mul_f32 v[34:35], v[8:9], v[34:35]
	v_pk_mul_f32 v[36:37], v[10:11], v[36:37]
	s_waitcnt vmcnt(4)
	v_pk_fma_f32 v[32:33], v[34:35], v[32:33], v[68:69]
	v_pk_mul_f32 v[34:35], v[42:43], v[80:81] op_sel_hi:[1,0]
	v_cvt_pk_bf16_f32 v32, v32, v33
	v_pk_fma_f32 v[34:35], v[36:37], v[34:35], v[70:71]
	s_waitcnt vmcnt(3)
	v_pk_add_f32 v[36:37], v[74:75], 1.0 op_sel_hi:[1,0]
	v_cvt_pk_bf16_f32 v33, v34, v35
	v_pk_add_f32 v[34:35], v[72:73], 1.0 op_sel_hi:[1,0]
	global_store_dwordx2 v[24:25], v[32:33], off
	v_pk_mul_f32 v[32:33], v[44:45], v[80:81] op_sel_hi:[1,0]
	v_pk_mul_f32 v[34:35], v[4:5], v[34:35]
	v_pk_mul_f32 v[36:37], v[6:7], v[36:37]
	s_waitcnt vmcnt(3)
	v_pk_fma_f32 v[32:33], v[34:35], v[32:33], v[76:77]
	v_pk_mul_f32 v[34:35], v[46:47], v[80:81] op_sel_hi:[1,0]
	v_cvt_pk_bf16_f32 v32, v32, v33
	v_pk_fma_f32 v[34:35], v[36:37], v[34:35], v[78:79]
	s_nop 0
	v_cvt_pk_bf16_f32 v33, v34, v35
	global_store_dwordx2 v[24:25], v[32:33], off offset:512
	v_lshl_add_u64 v[24:25], v[24:25], 0, s[10:11]
	s_andn2_b64 exec, exec, s[12:13]
	s_cbranch_execnz .LBB0_44

.LBB0_316:
	s_and_b64 vcc, exec, s[0:1]
	s_cbranch_vccz .LBB0_350
	v_and_b32_e32 v2, 0x7c, v136
	v_lshlrev_b32_e32 v140, 2, v2
	global_load_dwordx4 v[132:135], v140, s[90:91]
	v_and_b32_e32 v137, 64, v190
	v_xor_b32_e32 v136, 1, v190
	v_add_u32_e32 v137, 64, v137
	v_cmp_lt_i32_e32 vcc, v136, v137
	s_lshl_b32 s0, s42, 2
	s_add_i32 s0, s0, s94
	v_cndmask_b32_e32 v136, v190, v136, vcc
	v_lshlrev_b32_e32 v143, 2, v136
	v_xor_b32_e32 v136, 2, v190
	v_cmp_lt_i32_e32 vcc, v136, v137
	s_ashr_i32 s1, s0, 31
	v_ashrrev_i32_e32 v142, 5, v156
	v_cndmask_b32_e32 v136, v190, v136, vcc
	v_lshlrev_b32_e32 v152, 2, v136
	v_xor_b32_e32 v136, 4, v190
	v_cmp_lt_i32_e32 vcc, v136, v137
	s_lshl_b64 s[4:5], s[0:1], 17
	s_movk_i32 s0, 0x210
	v_cndmask_b32_e32 v136, v190, v136, vcc
	v_lshlrev_b32_e32 v153, 2, v136
	v_xor_b32_e32 v136, 8, v190
	v_cmp_lt_i32_e32 vcc, v136, v137
	s_nop 1
	v_cndmask_b32_e32 v136, v190, v136, vcc
	v_lshlrev_b32_e32 v155, 2, v136
	v_xor_b32_e32 v136, 16, v190
	v_cmp_lt_i32_e32 vcc, v136, v137
	s_nop 1
	v_cndmask_b32_e32 v136, v190, v136, vcc
	v_lshlrev_b32_e32 v154, 2, v136
	v_mul_lo_u32 v136, v142, s0
	v_add_u32_e32 v157, v140, v136
	ds_read_b128 v[136:139], v157
	s_waitcnt lgkmcnt(0)
	v_pk_mul_f32 v[160:161], v[136:137], v[136:137]
	v_pk_mul_f32 v[158:159], v[138:139], v[138:139]
	v_add_f32_e32 v141, v160, v161
	v_add_f32_e32 v141, v158, v141
	v_add_f32_e32 v141, v159, v141
	s_nop 1
	s_waitcnt lgkmcnt(0)
	v_add_f32_dpp v141, v141, v141 quad_perm:[1,0,3,2] row_mask:0xf bank_mask:0xf
	s_nop 1
	s_waitcnt lgkmcnt(0)
	v_add_f32_dpp v141, v141, v141 quad_perm:[2,3,0,1] row_mask:0xf bank_mask:0xf
	s_nop 1
	s_waitcnt lgkmcnt(0)
	v_add_f32_dpp v141, v141, v141 row_half_mirror row_mask:0xf bank_mask:0xf
	s_nop 1
	s_waitcnt lgkmcnt(0)
	v_add_f32_dpp v141, v141, v141 row_mirror row_mask:0xf bank_mask:0xf
	v_mov_b32_e32 v158, v141
	s_nop 1
	v_permlane16_swap_b32_e32 v158, v141
	s_waitcnt lgkmcnt(0)
	v_add_f32_e32 v141, v141, v158
	v_fmamk_f32 v141, v141, 0x3c000000, v1
	v_cmp_gt_f32_e32 vcc, s29, v141
	v_mul_f32_e32 v158, 0x4b800000, v141
	s_nop 0
	v_cndmask_b32_e32 v141, v141, v158, vcc
	v_rsq_f32_e32 v141, v141
	s_nop 0
	v_mul_f32_e32 v158, 0x45800000, v141
	v_cndmask_b32_e32 v158, v141, v158, vcc
	v_pk_mul_f32 v[136:137], v[136:137], v[158:159] op_sel_hi:[1,0]
	v_pk_mul_f32 v[138:139], v[138:139], v[158:159] op_sel_hi:[1,0]
	v_cndmask_b32_e64 v141, 0, 1, s[2:3]
	s_waitcnt vmcnt(0)
	v_pk_mul_f32 v[136:137], v[132:133], v[136:137]
	v_pk_mul_f32 v[138:139], v[134:135], v[138:139]
	v_cmp_ne_u32_e64 s[38:39], 1, v141
	s_andn2_b64 vcc, exec, s[2:3]
	s_cbranch_vccnz .LBB0_319
	v_add_u32_e32 v158, s6, v142
	v_readlane_b32 s0, v251, 28
	v_ashrrev_i32_e32 v159, 31, v158
	s_add_u32 s0, s0, s4
	v_readlane_b32 s1, v251, 29
	s_addc_u32 s1, s1, s5
	v_lshlrev_b64 v[158:159], 9, v[158:159]
	v_lshl_add_u64 v[158:159], s[0:1], 0, v[158:159]
	v_mov_b32_e32 v141, v3
	v_lshl_add_u64 v[158:159], v[158:159], 0, v[140:141]
	global_store_dwordx4 v[158:159], v[136:139], off
.LBB0_319:
	v_add_u32_e32 v158, s83, v142
	v_ashrrev_i32_e32 v159, 31, v158
	v_readlane_b32 s12, v253, 2
	v_lshlrev_b64 v[158:159], 8, v[158:159]
	v_readlane_b32 s18, v253, 8
	v_readlane_b32 s19, v253, 9
	v_lshlrev_b32_e32 v2, 1, v2
	v_cvt_pk_bf16_f32 v136, v136, v137
	v_lshl_add_u64 v[158:159], s[18:19], 0, v[158:159]
	v_lshl_add_u64 v[158:159], v[158:159], 0, v[2:3]
	v_cvt_pk_bf16_f32 v137, v138, v139
	global_store_dwordx2 v[158:159], v[136:137], off
	ds_read_b128 v[136:139], v157 offset:4224
	v_add_u32_e32 v158, 8, v142
	v_readlane_b32 s13, v253, 3
	v_readlane_b32 s14, v253, 4
	v_readlane_b32 s15, v253, 5
	s_waitcnt lgkmcnt(0)
	v_pk_mul_f32 v[162:163], v[136:137], v[136:137]
	v_pk_mul_f32 v[160:161], v[138:139], v[138:139]
	v_add_f32_e32 v141, v162, v163
	v_add_f32_e32 v141, v160, v141
	v_add_f32_e32 v141, v161, v141
	s_nop 1
	v_readlane_b32 s16, v253, 6
	v_readlane_b32 s17, v253, 7
	s_waitcnt lgkmcnt(0)
	v_add_f32_dpp v141, v141, v141 quad_perm:[1,0,3,2] row_mask:0xf bank_mask:0xf
	s_nop 1
	s_waitcnt lgkmcnt(0)
	v_add_f32_dpp v141, v141, v141 quad_perm:[2,3,0,1] row_mask:0xf bank_mask:0xf
	s_nop 1
	s_waitcnt lgkmcnt(0)
	v_add_f32_dpp v141, v141, v141 row_half_mirror row_mask:0xf bank_mask:0xf
	s_nop 1
	s_waitcnt lgkmcnt(0)
	v_add_f32_dpp v141, v141, v141 row_mirror row_mask:0xf bank_mask:0xf
	v_mov_b32_e32 v159, v141
	s_nop 1
	v_permlane16_swap_b32_e32 v159, v141
	s_waitcnt lgkmcnt(0)
	v_add_f32_e32 v141, v141, v159
	v_fmamk_f32 v141, v141, 0x3c000000, v1
	v_cmp_gt_f32_e32 vcc, s29, v141
	v_mul_f32_e32 v159, 0x4b800000, v141
	s_nop 0
	v_cndmask_b32_e32 v141, v141, v159, vcc
	v_rsq_f32_e32 v141, v141
	s_nop 0
	v_mul_f32_e32 v159, 0x45800000, v141
	v_cndmask_b32_e32 v160, v141, v159, vcc
	v_pk_mul_f32 v[136:137], v[136:137], v[160:161] op_sel_hi:[1,0]
	v_pk_mul_f32 v[138:139], v[138:139], v[160:161] op_sel_hi:[1,0]
	v_pk_mul_f32 v[136:137], v[132:133], v[136:137]
	v_pk_mul_f32 v[138:139], v[134:135], v[138:139]
	s_and_b64 vcc, exec, s[38:39]
	s_cbranch_vccnz .LBB0_321
	v_add_u32_e32 v160, s6, v158
	v_readlane_b32 s0, v251, 28
	v_ashrrev_i32_e32 v161, 31, v160
	s_add_u32 s0, s0, s4
	v_readlane_b32 s1, v251, 29
	s_addc_u32 s1, s1, s5
	v_lshlrev_b64 v[160:161], 9, v[160:161]
	v_lshl_add_u64 v[160:161], s[0:1], 0, v[160:161]
	v_mov_b32_e32 v141, v3
	v_lshl_add_u64 v[160:161], v[160:161], 0, v[140:141]
	global_store_dwordx4 v[160:161], v[136:139], off
.LBB0_321:
	v_add_u32_e32 v158, s83, v158
	v_ashrrev_i32_e32 v159, 31, v158
	v_readlane_b32 s12, v253, 2
	v_lshlrev_b64 v[158:159], 8, v[158:159]
	v_readlane_b32 s18, v253, 8
	v_readlane_b32 s19, v253, 9
	v_cvt_pk_bf16_f32 v136, v136, v137
	v_cvt_pk_bf16_f32 v137, v138, v139
	v_lshl_add_u64 v[158:159], s[18:19], 0, v[158:159]
	v_lshl_add_u64 v[158:159], v[158:159], 0, v[2:3]
	global_store_dwordx2 v[158:159], v[136:137], off
	ds_read_b128 v[136:139], v157 offset:8448
	v_add_u32_e32 v158, 16, v142
	v_readlane_b32 s13, v253, 3
	v_readlane_b32 s14, v253, 4
	v_readlane_b32 s15, v253, 5
	s_waitcnt lgkmcnt(0)
	v_pk_mul_f32 v[162:163], v[136:137], v[136:137]
	v_pk_mul_f32 v[160:161], v[138:139], v[138:139]
	v_add_f32_e32 v141, v162, v163
	v_add_f32_e32 v141, v160, v141
	v_add_f32_e32 v141, v161, v141
	s_nop 1
	v_readlane_b32 s16, v253, 6
	v_readlane_b32 s17, v253, 7
	s_waitcnt lgkmcnt(0)
	v_add_f32_dpp v141, v141, v141 quad_perm:[1,0,3,2] row_mask:0xf bank_mask:0xf
	s_nop 1
	s_waitcnt lgkmcnt(0)
	v_add_f32_dpp v141, v141, v141 quad_perm:[2,3,0,1] row_mask:0xf bank_mask:0xf
	s_nop 1
	s_waitcnt lgkmcnt(0)
	v_add_f32_dpp v141, v141, v141 row_half_mirror row_mask:0xf bank_mask:0xf
	s_nop 1
	s_waitcnt lgkmcnt(0)
	v_add_f32_dpp v141, v141, v141 row_mirror row_mask:0xf bank_mask:0xf
	v_mov_b32_e32 v159, v141
	s_nop 1
	v_permlane16_swap_b32_e32 v159, v141
	s_waitcnt lgkmcnt(0)
	v_add_f32_e32 v141, v141, v159
	v_fmamk_f32 v141, v141, 0x3c000000, v1
	v_cmp_gt_f32_e32 vcc, s29, v141
	v_mul_f32_e32 v159, 0x4b800000, v141
	s_nop 0
	v_cndmask_b32_e32 v141, v141, v159, vcc
	v_rsq_f32_e32 v141, v141
	s_nop 0
	v_mul_f32_e32 v159, 0x45800000, v141
	v_cndmask_b32_e32 v160, v141, v159, vcc
	v_pk_mul_f32 v[136:137], v[136:137], v[160:161] op_sel_hi:[1,0]
	v_pk_mul_f32 v[138:139], v[138:139], v[160:161] op_sel_hi:[1,0]
	v_pk_mul_f32 v[136:137], v[132:133], v[136:137]
	v_pk_mul_f32 v[138:139], v[134:135], v[138:139]
	s_and_b64 vcc, exec, s[38:39]
	s_cbranch_vccnz .LBB0_323
	v_add_u32_e32 v160, s6, v158
	v_readlane_b32 s0, v251, 28
	v_ashrrev_i32_e32 v161, 31, v160
	s_add_u32 s0, s0, s4
	v_readlane_b32 s1, v251, 29
	s_addc_u32 s1, s1, s5
	v_lshlrev_b64 v[160:161], 9, v[160:161]
	v_lshl_add_u64 v[160:161], s[0:1], 0, v[160:161]
	v_mov_b32_e32 v141, v3
	v_lshl_add_u64 v[160:161], v[160:161], 0, v[140:141]
	global_store_dwordx4 v[160:161], v[136:139], off
.LBB0_323:
	v_add_u32_e32 v158, s83, v158
	v_ashrrev_i32_e32 v159, 31, v158
	v_readlane_b32 s12, v253, 2
	v_lshlrev_b64 v[158:159], 8, v[158:159]
	v_readlane_b32 s18, v253, 8
	v_readlane_b32 s19, v253, 9
	v_cvt_pk_bf16_f32 v136, v136, v137
	v_cvt_pk_bf16_f32 v137, v138, v139
	v_lshl_add_u64 v[158:159], s[18:19], 0, v[158:159]
	v_lshl_add_u64 v[158:159], v[158:159], 0, v[2:3]
	global_store_dwordx2 v[158:159], v[136:137], off
	ds_read_b128 v[136:139], v157 offset:12672
	v_add_u32_e32 v158, 24, v142
	v_readlane_b32 s13, v253, 3
	v_readlane_b32 s14, v253, 4
	v_readlane_b32 s15, v253, 5
	s_waitcnt lgkmcnt(0)
	v_pk_mul_f32 v[162:163], v[136:137], v[136:137]
	v_pk_mul_f32 v[160:161], v[138:139], v[138:139]
	v_add_f32_e32 v141, v162, v163
	v_add_f32_e32 v141, v160, v141
	v_add_f32_e32 v141, v161, v141
	s_nop 1
	v_readlane_b32 s16, v253, 6
	v_readlane_b32 s17, v253, 7
	s_waitcnt lgkmcnt(0)
	v_add_f32_dpp v141, v141, v141 quad_perm:[1,0,3,2] row_mask:0xf bank_mask:0xf
	s_nop 1
	s_waitcnt lgkmcnt(0)
	v_add_f32_dpp v141, v141, v141 quad_perm:[2,3,0,1] row_mask:0xf bank_mask:0xf
	s_nop 1
	s_waitcnt lgkmcnt(0)
	v_add_f32_dpp v141, v141, v141 row_half_mirror row_mask:0xf bank_mask:0xf
	s_nop 1
	s_waitcnt lgkmcnt(0)
	v_add_f32_dpp v141, v141, v141 row_mirror row_mask:0xf bank_mask:0xf
	v_mov_b32_e32 v159, v141
	s_nop 1
	v_permlane16_swap_b32_e32 v159, v141
	s_waitcnt lgkmcnt(0)
	v_add_f32_e32 v141, v141, v159
	v_fmamk_f32 v141, v141, 0x3c000000, v1
	v_cmp_gt_f32_e32 vcc, s29, v141
	v_mul_f32_e32 v159, 0x4b800000, v141
	s_nop 0
	v_cndmask_b32_e32 v141, v141, v159, vcc
	v_rsq_f32_e32 v141, v141
	s_nop 0
	v_mul_f32_e32 v159, 0x45800000, v141
	v_cndmask_b32_e32 v160, v141, v159, vcc
	v_pk_mul_f32 v[136:137], v[136:137], v[160:161] op_sel_hi:[1,0]
	v_pk_mul_f32 v[138:139], v[138:139], v[160:161] op_sel_hi:[1,0]
	v_pk_mul_f32 v[136:137], v[132:133], v[136:137]
	v_pk_mul_f32 v[138:139], v[134:135], v[138:139]
	s_and_b64 vcc, exec, s[38:39]
	s_cbranch_vccnz .LBB0_325
	v_add_u32_e32 v160, s6, v158
	v_readlane_b32 s0, v251, 28
	v_ashrrev_i32_e32 v161, 31, v160
	s_add_u32 s0, s0, s4
	v_readlane_b32 s1, v251, 29
	s_addc_u32 s1, s1, s5
	v_lshlrev_b64 v[160:161], 9, v[160:161]
	v_lshl_add_u64 v[160:161], s[0:1], 0, v[160:161]
	v_mov_b32_e32 v141, v3
	v_lshl_add_u64 v[160:161], v[160:161], 0, v[140:141]
	global_store_dwordx4 v[160:161], v[136:139], off
.LBB0_325:
	v_add_u32_e32 v158, s83, v158
	v_ashrrev_i32_e32 v159, 31, v158
	v_readlane_b32 s12, v253, 2
	v_lshlrev_b64 v[158:159], 8, v[158:159]
	v_readlane_b32 s18, v253, 8
	v_readlane_b32 s19, v253, 9
	v_cvt_pk_bf16_f32 v136, v136, v137
	v_cvt_pk_bf16_f32 v137, v138, v139
	v_lshl_add_u64 v[158:159], s[18:19], 0, v[158:159]
	v_lshl_add_u64 v[158:159], v[158:159], 0, v[2:3]
	global_store_dwordx2 v[158:159], v[136:137], off
	ds_read_b128 v[136:139], v157 offset:16896
	v_add_u32_e32 v158, 32, v142
	v_readlane_b32 s13, v253, 3
	v_readlane_b32 s14, v253, 4
	v_readlane_b32 s15, v253, 5
	s_waitcnt lgkmcnt(0)
	v_pk_mul_f32 v[162:163], v[136:137], v[136:137]
	v_pk_mul_f32 v[160:161], v[138:139], v[138:139]
	v_add_f32_e32 v141, v162, v163
	v_add_f32_e32 v141, v160, v141
	v_add_f32_e32 v141, v161, v141
	s_nop 1
	v_readlane_b32 s16, v253, 6
	v_readlane_b32 s17, v253, 7
	s_waitcnt lgkmcnt(0)
	v_add_f32_dpp v141, v141, v141 quad_perm:[1,0,3,2] row_mask:0xf bank_mask:0xf
	s_nop 1
	s_waitcnt lgkmcnt(0)
	v_add_f32_dpp v141, v141, v141 quad_perm:[2,3,0,1] row_mask:0xf bank_mask:0xf
	s_nop 1
	s_waitcnt lgkmcnt(0)
	v_add_f32_dpp v141, v141, v141 row_half_mirror row_mask:0xf bank_mask:0xf
	s_nop 1
	s_waitcnt lgkmcnt(0)
	v_add_f32_dpp v141, v141, v141 row_mirror row_mask:0xf bank_mask:0xf
	v_mov_b32_e32 v159, v141
	s_nop 1
	v_permlane16_swap_b32_e32 v159, v141
	s_waitcnt lgkmcnt(0)
	v_add_f32_e32 v141, v141, v159
	v_fmamk_f32 v141, v141, 0x3c000000, v1
	v_cmp_gt_f32_e32 vcc, s29, v141
	v_mul_f32_e32 v159, 0x4b800000, v141
	s_nop 0
	v_cndmask_b32_e32 v141, v141, v159, vcc
	v_rsq_f32_e32 v141, v141
	s_nop 0
	v_mul_f32_e32 v159, 0x45800000, v141
	v_cndmask_b32_e32 v160, v141, v159, vcc
	v_pk_mul_f32 v[136:137], v[136:137], v[160:161] op_sel_hi:[1,0]
	v_pk_mul_f32 v[138:139], v[138:139], v[160:161] op_sel_hi:[1,0]
	v_pk_mul_f32 v[136:137], v[132:133], v[136:137]
	v_pk_mul_f32 v[138:139], v[134:135], v[138:139]
	s_and_b64 vcc, exec, s[38:39]
	s_cbranch_vccnz .LBB0_327
	v_add_u32_e32 v160, s6, v158
	v_readlane_b32 s0, v251, 28
	v_ashrrev_i32_e32 v161, 31, v160
	s_add_u32 s0, s0, s4
	v_readlane_b32 s1, v251, 29
	s_addc_u32 s1, s1, s5
	v_lshlrev_b64 v[160:161], 9, v[160:161]
	v_lshl_add_u64 v[160:161], s[0:1], 0, v[160:161]
	v_mov_b32_e32 v141, v3
	v_lshl_add_u64 v[160:161], v[160:161], 0, v[140:141]
	global_store_dwordx4 v[160:161], v[136:139], off
.LBB0_327:
	v_add_u32_e32 v158, s83, v158
	v_ashrrev_i32_e32 v159, 31, v158
	v_readlane_b32 s12, v253, 2
	v_lshlrev_b64 v[158:159], 8, v[158:159]
	v_readlane_b32 s18, v253, 8
	v_readlane_b32 s19, v253, 9
	v_cvt_pk_bf16_f32 v136, v136, v137
	v_cvt_pk_bf16_f32 v137, v138, v139
	v_lshl_add_u64 v[158:159], s[18:19], 0, v[158:159]
	v_lshl_add_u64 v[158:159], v[158:159], 0, v[2:3]
	global_store_dwordx2 v[158:159], v[136:137], off
	ds_read_b128 v[136:139], v157 offset:21120
	v_add_u32_e32 v158, 40, v142
	v_readlane_b32 s13, v253, 3
	v_readlane_b32 s14, v253, 4
	v_readlane_b32 s15, v253, 5
	s_waitcnt lgkmcnt(0)
	v_pk_mul_f32 v[162:163], v[136:137], v[136:137]
	v_pk_mul_f32 v[160:161], v[138:139], v[138:139]
	v_add_f32_e32 v141, v162, v163
	v_add_f32_e32 v141, v160, v141
	v_add_f32_e32 v141, v161, v141
	s_nop 1
	v_readlane_b32 s16, v253, 6
	v_readlane_b32 s17, v253, 7
	s_waitcnt lgkmcnt(0)
	v_add_f32_dpp v141, v141, v141 quad_perm:[1,0,3,2] row_mask:0xf bank_mask:0xf
	s_nop 1
	s_waitcnt lgkmcnt(0)
	v_add_f32_dpp v141, v141, v141 quad_perm:[2,3,0,1] row_mask:0xf bank_mask:0xf
	s_nop 1
	s_waitcnt lgkmcnt(0)
	v_add_f32_dpp v141, v141, v141 row_half_mirror row_mask:0xf bank_mask:0xf
	s_nop 1
	s_waitcnt lgkmcnt(0)
	v_add_f32_dpp v141, v141, v141 row_mirror row_mask:0xf bank_mask:0xf
	v_mov_b32_e32 v159, v141
	s_nop 1
	v_permlane16_swap_b32_e32 v159, v141
	s_waitcnt lgkmcnt(0)
	v_add_f32_e32 v141, v141, v159
	v_fmamk_f32 v141, v141, 0x3c000000, v1
	v_cmp_gt_f32_e32 vcc, s29, v141
	v_mul_f32_e32 v159, 0x4b800000, v141
	s_nop 0
	v_cndmask_b32_e32 v141, v141, v159, vcc
	v_rsq_f32_e32 v141, v141
	s_nop 0
	v_mul_f32_e32 v159, 0x45800000, v141
	v_cndmask_b32_e32 v160, v141, v159, vcc
	v_pk_mul_f32 v[136:137], v[136:137], v[160:161] op_sel_hi:[1,0]
	v_pk_mul_f32 v[138:139], v[138:139], v[160:161] op_sel_hi:[1,0]
	v_pk_mul_f32 v[136:137], v[132:133], v[136:137]
	v_pk_mul_f32 v[138:139], v[134:135], v[138:139]
	s_and_b64 vcc, exec, s[38:39]
	s_cbranch_vccnz .LBB0_329
	v_add_u32_e32 v160, s6, v158
	v_readlane_b32 s0, v251, 28
	v_ashrrev_i32_e32 v161, 31, v160
	s_add_u32 s0, s0, s4
	v_readlane_b32 s1, v251, 29
	s_addc_u32 s1, s1, s5
	v_lshlrev_b64 v[160:161], 9, v[160:161]
	v_lshl_add_u64 v[160:161], s[0:1], 0, v[160:161]
	v_mov_b32_e32 v141, v3
	v_lshl_add_u64 v[160:161], v[160:161], 0, v[140:141]
	global_store_dwordx4 v[160:161], v[136:139], off
.LBB0_329:
	v_add_u32_e32 v158, s83, v158
	v_ashrrev_i32_e32 v159, 31, v158
	v_readlane_b32 s12, v253, 2
	v_lshlrev_b64 v[158:159], 8, v[158:159]
	v_readlane_b32 s18, v253, 8
	v_readlane_b32 s19, v253, 9
	v_cvt_pk_bf16_f32 v136, v136, v137
	v_cvt_pk_bf16_f32 v137, v138, v139
	v_lshl_add_u64 v[158:159], s[18:19], 0, v[158:159]
	v_lshl_add_u64 v[158:159], v[158:159], 0, v[2:3]
	global_store_dwordx2 v[158:159], v[136:137], off
	ds_read_b128 v[136:139], v157 offset:25344
	v_add_u32_e32 v158, 48, v142
	v_readlane_b32 s13, v253, 3
	v_readlane_b32 s14, v253, 4
	v_readlane_b32 s15, v253, 5
	s_waitcnt lgkmcnt(0)
	v_pk_mul_f32 v[162:163], v[136:137], v[136:137]
	v_pk_mul_f32 v[160:161], v[138:139], v[138:139]
	v_add_f32_e32 v141, v162, v163
	v_add_f32_e32 v141, v160, v141
	v_add_f32_e32 v141, v161, v141
	s_nop 1
	v_readlane_b32 s16, v253, 6
	v_readlane_b32 s17, v253, 7
	s_waitcnt lgkmcnt(0)
	v_add_f32_dpp v141, v141, v141 quad_perm:[1,0,3,2] row_mask:0xf bank_mask:0xf
	s_nop 1
	s_waitcnt lgkmcnt(0)
	v_add_f32_dpp v141, v141, v141 quad_perm:[2,3,0,1] row_mask:0xf bank_mask:0xf
	s_nop 1
	s_waitcnt lgkmcnt(0)
	v_add_f32_dpp v141, v141, v141 row_half_mirror row_mask:0xf bank_mask:0xf
	s_nop 1
	s_waitcnt lgkmcnt(0)
	v_add_f32_dpp v141, v141, v141 row_mirror row_mask:0xf bank_mask:0xf
	v_mov_b32_e32 v159, v141
	s_nop 1
	v_permlane16_swap_b32_e32 v159, v141
	s_waitcnt lgkmcnt(0)
	v_add_f32_e32 v141, v141, v159
	v_fmamk_f32 v141, v141, 0x3c000000, v1
	v_cmp_gt_f32_e32 vcc, s29, v141
	v_mul_f32_e32 v159, 0x4b800000, v141
	s_nop 0
	v_cndmask_b32_e32 v141, v141, v159, vcc
	v_rsq_f32_e32 v141, v141
	s_nop 0
	v_mul_f32_e32 v159, 0x45800000, v141
	v_cndmask_b32_e32 v160, v141, v159, vcc
	v_pk_mul_f32 v[136:137], v[136:137], v[160:161] op_sel_hi:[1,0]
	v_pk_mul_f32 v[138:139], v[138:139], v[160:161] op_sel_hi:[1,0]
	v_pk_mul_f32 v[136:137], v[132:133], v[136:137]
	v_pk_mul_f32 v[138:139], v[134:135], v[138:139]
	s_and_b64 vcc, exec, s[38:39]
	s_cbranch_vccnz .LBB0_331
	v_add_u32_e32 v160, s6, v158
	v_readlane_b32 s0, v251, 28
	v_ashrrev_i32_e32 v161, 31, v160
	s_add_u32 s0, s0, s4
	v_readlane_b32 s1, v251, 29
	s_addc_u32 s1, s1, s5
	v_lshlrev_b64 v[160:161], 9, v[160:161]
	v_lshl_add_u64 v[160:161], s[0:1], 0, v[160:161]
	v_mov_b32_e32 v141, v3
	v_lshl_add_u64 v[160:161], v[160:161], 0, v[140:141]
	global_store_dwordx4 v[160:161], v[136:139], off
.LBB0_331:
	v_add_u32_e32 v158, s83, v158
	v_ashrrev_i32_e32 v159, 31, v158
	v_readlane_b32 s12, v253, 2
	v_lshlrev_b64 v[158:159], 8, v[158:159]
	v_readlane_b32 s18, v253, 8
	v_readlane_b32 s19, v253, 9
	v_cvt_pk_bf16_f32 v136, v136, v137
	v_cvt_pk_bf16_f32 v137, v138, v139
	v_lshl_add_u64 v[158:159], s[18:19], 0, v[158:159]
	v_lshl_add_u64 v[158:159], v[158:159], 0, v[2:3]
	global_store_dwordx2 v[158:159], v[136:137], off
	ds_read_b128 v[136:139], v157 offset:29568
	v_add_u32_e32 v158, 56, v142
	v_readlane_b32 s13, v253, 3
	v_readlane_b32 s14, v253, 4
	v_readlane_b32 s15, v253, 5
	s_waitcnt lgkmcnt(0)
	v_pk_mul_f32 v[162:163], v[136:137], v[136:137]
	v_pk_mul_f32 v[160:161], v[138:139], v[138:139]
	v_add_f32_e32 v141, v162, v163
	v_add_f32_e32 v141, v160, v141
	v_add_f32_e32 v141, v161, v141
	s_nop 1
	v_readlane_b32 s16, v253, 6
	v_readlane_b32 s17, v253, 7
	s_waitcnt lgkmcnt(0)
	v_add_f32_dpp v141, v141, v141 quad_perm:[1,0,3,2] row_mask:0xf bank_mask:0xf
	s_nop 1
	s_waitcnt lgkmcnt(0)
	v_add_f32_dpp v141, v141, v141 quad_perm:[2,3,0,1] row_mask:0xf bank_mask:0xf
	s_nop 1
	s_waitcnt lgkmcnt(0)
	v_add_f32_dpp v141, v141, v141 row_half_mirror row_mask:0xf bank_mask:0xf
	s_nop 1
	s_waitcnt lgkmcnt(0)
	v_add_f32_dpp v141, v141, v141 row_mirror row_mask:0xf bank_mask:0xf
	v_mov_b32_e32 v159, v141
	s_nop 1
	v_permlane16_swap_b32_e32 v159, v141
	s_waitcnt lgkmcnt(0)
	v_add_f32_e32 v141, v141, v159
	v_fmamk_f32 v141, v141, 0x3c000000, v1
	v_cmp_gt_f32_e32 vcc, s29, v141
	v_mul_f32_e32 v159, 0x4b800000, v141
	s_nop 0
	v_cndmask_b32_e32 v141, v141, v159, vcc
	v_rsq_f32_e32 v141, v141
	s_nop 0
	v_mul_f32_e32 v159, 0x45800000, v141
	v_cndmask_b32_e32 v160, v141, v159, vcc
	v_pk_mul_f32 v[136:137], v[136:137], v[160:161] op_sel_hi:[1,0]
	v_pk_mul_f32 v[138:139], v[138:139], v[160:161] op_sel_hi:[1,0]
	v_pk_mul_f32 v[136:137], v[132:133], v[136:137]
	v_pk_mul_f32 v[138:139], v[134:135], v[138:139]
	s_and_b64 vcc, exec, s[38:39]
	s_cbranch_vccnz .LBB0_333
	v_add_u32_e32 v160, s6, v158
	v_readlane_b32 s0, v251, 28
	v_ashrrev_i32_e32 v161, 31, v160
	s_add_u32 s0, s0, s4
	v_readlane_b32 s1, v251, 29
	s_addc_u32 s1, s1, s5
	v_lshlrev_b64 v[160:161], 9, v[160:161]
	v_lshl_add_u64 v[160:161], s[0:1], 0, v[160:161]
	v_mov_b32_e32 v141, v3
	v_lshl_add_u64 v[160:161], v[160:161], 0, v[140:141]
	global_store_dwordx4 v[160:161], v[136:139], off
.LBB0_333:
	v_add_u32_e32 v158, s83, v158
	v_ashrrev_i32_e32 v159, 31, v158
	v_readlane_b32 s12, v253, 2
	v_lshlrev_b64 v[158:159], 8, v[158:159]
	v_readlane_b32 s18, v253, 8
	v_readlane_b32 s19, v253, 9
	v_cvt_pk_bf16_f32 v136, v136, v137
	v_cvt_pk_bf16_f32 v137, v138, v139
	v_lshl_add_u64 v[158:159], s[18:19], 0, v[158:159]
	v_lshl_add_u64 v[158:159], v[158:159], 0, v[2:3]
	global_store_dwordx2 v[158:159], v[136:137], off
	ds_read_b128 v[136:139], v157 offset:33792
	v_add_u32_e32 v158, 64, v142
	v_readlane_b32 s13, v253, 3
	v_readlane_b32 s14, v253, 4
	v_readlane_b32 s15, v253, 5
	s_waitcnt lgkmcnt(0)
	v_pk_mul_f32 v[162:163], v[136:137], v[136:137]
	v_pk_mul_f32 v[160:161], v[138:139], v[138:139]
	v_add_f32_e32 v141, v162, v163
	v_add_f32_e32 v141, v160, v141
	v_add_f32_e32 v141, v161, v141
	s_nop 1
	v_readlane_b32 s16, v253, 6
	v_readlane_b32 s17, v253, 7
	s_waitcnt lgkmcnt(0)
	v_add_f32_dpp v141, v141, v141 quad_perm:[1,0,3,2] row_mask:0xf bank_mask:0xf
	s_nop 1
	s_waitcnt lgkmcnt(0)
	v_add_f32_dpp v141, v141, v141 quad_perm:[2,3,0,1] row_mask:0xf bank_mask:0xf
	s_nop 1
	s_waitcnt lgkmcnt(0)
	v_add_f32_dpp v141, v141, v141 row_half_mirror row_mask:0xf bank_mask:0xf
	s_nop 1
	s_waitcnt lgkmcnt(0)
	v_add_f32_dpp v141, v141, v141 row_mirror row_mask:0xf bank_mask:0xf
	v_mov_b32_e32 v159, v141
	s_nop 1
	v_permlane16_swap_b32_e32 v159, v141
	s_waitcnt lgkmcnt(0)
	v_add_f32_e32 v141, v141, v159
	v_fmamk_f32 v141, v141, 0x3c000000, v1
	v_cmp_gt_f32_e32 vcc, s29, v141
	v_mul_f32_e32 v159, 0x4b800000, v141
	s_nop 0
	v_cndmask_b32_e32 v141, v141, v159, vcc
	v_rsq_f32_e32 v141, v141
	s_nop 0
	v_mul_f32_e32 v159, 0x45800000, v141
	v_cndmask_b32_e32 v160, v141, v159, vcc
	v_pk_mul_f32 v[136:137], v[136:137], v[160:161] op_sel_hi:[1,0]
	v_pk_mul_f32 v[138:139], v[138:139], v[160:161] op_sel_hi:[1,0]
	v_pk_mul_f32 v[136:137], v[132:133], v[136:137]
	v_pk_mul_f32 v[138:139], v[134:135], v[138:139]
	s_and_b64 vcc, exec, s[38:39]
	s_cbranch_vccnz .LBB0_335
	v_add_u32_e32 v160, s6, v158
	v_readlane_b32 s0, v251, 28
	v_ashrrev_i32_e32 v161, 31, v160
	s_add_u32 s0, s0, s4
	v_readlane_b32 s1, v251, 29
	s_addc_u32 s1, s1, s5
	v_lshlrev_b64 v[160:161], 9, v[160:161]
	v_lshl_add_u64 v[160:161], s[0:1], 0, v[160:161]
	v_mov_b32_e32 v141, v3
	v_lshl_add_u64 v[160:161], v[160:161], 0, v[140:141]
	global_store_dwordx4 v[160:161], v[136:139], off
.LBB0_335:
	v_add_u32_e32 v158, s83, v158
	v_ashrrev_i32_e32 v159, 31, v158
	v_readlane_b32 s12, v253, 2
	v_lshlrev_b64 v[158:159], 8, v[158:159]
	v_readlane_b32 s18, v253, 8
	v_readlane_b32 s19, v253, 9
	v_cvt_pk_bf16_f32 v136, v136, v137
	v_cvt_pk_bf16_f32 v137, v138, v139
	v_lshl_add_u64 v[158:159], s[18:19], 0, v[158:159]
	v_lshl_add_u64 v[158:159], v[158:159], 0, v[2:3]
	global_store_dwordx2 v[158:159], v[136:137], off
	ds_read_b128 v[136:139], v157 offset:38016
	v_add_u32_e32 v158, 0x48, v142
	v_readlane_b32 s13, v253, 3
	v_readlane_b32 s14, v253, 4
	v_readlane_b32 s15, v253, 5
	s_waitcnt lgkmcnt(0)
	v_pk_mul_f32 v[162:163], v[136:137], v[136:137]
	v_pk_mul_f32 v[160:161], v[138:139], v[138:139]
	v_add_f32_e32 v141, v162, v163
	v_add_f32_e32 v141, v160, v141
	v_add_f32_e32 v141, v161, v141
	s_nop 1
	v_readlane_b32 s16, v253, 6
	v_readlane_b32 s17, v253, 7
	s_waitcnt lgkmcnt(0)
	v_add_f32_dpp v141, v141, v141 quad_perm:[1,0,3,2] row_mask:0xf bank_mask:0xf
	s_nop 1
	s_waitcnt lgkmcnt(0)
	v_add_f32_dpp v141, v141, v141 quad_perm:[2,3,0,1] row_mask:0xf bank_mask:0xf
	s_nop 1
	s_waitcnt lgkmcnt(0)
	v_add_f32_dpp v141, v141, v141 row_half_mirror row_mask:0xf bank_mask:0xf
	s_nop 1
	s_waitcnt lgkmcnt(0)
	v_add_f32_dpp v141, v141, v141 row_mirror row_mask:0xf bank_mask:0xf
	v_mov_b32_e32 v159, v141
	s_nop 1
	v_permlane16_swap_b32_e32 v159, v141
	s_waitcnt lgkmcnt(0)
	v_add_f32_e32 v141, v141, v159
	v_fmamk_f32 v141, v141, 0x3c000000, v1
	v_cmp_gt_f32_e32 vcc, s29, v141
	v_mul_f32_e32 v159, 0x4b800000, v141
	s_nop 0
	v_cndmask_b32_e32 v141, v141, v159, vcc
	v_rsq_f32_e32 v141, v141
	s_nop 0
	v_mul_f32_e32 v159, 0x45800000, v141
	v_cndmask_b32_e32 v160, v141, v159, vcc
	v_pk_mul_f32 v[136:137], v[136:137], v[160:161] op_sel_hi:[1,0]
	v_pk_mul_f32 v[138:139], v[138:139], v[160:161] op_sel_hi:[1,0]
	v_pk_mul_f32 v[136:137], v[132:133], v[136:137]
	v_pk_mul_f32 v[138:139], v[134:135], v[138:139]
	s_and_b64 vcc, exec, s[38:39]
	s_cbranch_vccnz .LBB0_337
	v_add_u32_e32 v160, s6, v158
	v_readlane_b32 s0, v251, 28
	v_ashrrev_i32_e32 v161, 31, v160
	s_add_u32 s0, s0, s4
	v_readlane_b32 s1, v251, 29
	s_addc_u32 s1, s1, s5
	v_lshlrev_b64 v[160:161], 9, v[160:161]
	v_lshl_add_u64 v[160:161], s[0:1], 0, v[160:161]
	v_mov_b32_e32 v141, v3
	v_lshl_add_u64 v[160:161], v[160:161], 0, v[140:141]
	global_store_dwordx4 v[160:161], v[136:139], off
.LBB0_337:
	v_add_u32_e32 v158, s83, v158
	v_ashrrev_i32_e32 v159, 31, v158
	v_readlane_b32 s12, v253, 2
	v_lshlrev_b64 v[158:159], 8, v[158:159]
	v_readlane_b32 s18, v253, 8
	v_readlane_b32 s19, v253, 9
	v_cvt_pk_bf16_f32 v136, v136, v137
	v_cvt_pk_bf16_f32 v137, v138, v139
	v_lshl_add_u64 v[158:159], s[18:19], 0, v[158:159]
	v_lshl_add_u64 v[158:159], v[158:159], 0, v[2:3]
	global_store_dwordx2 v[158:159], v[136:137], off
	ds_read_b128 v[136:139], v157 offset:42240
	v_add_u32_e32 v158, 0x50, v142
	v_readlane_b32 s13, v253, 3
	v_readlane_b32 s14, v253, 4
	v_readlane_b32 s15, v253, 5
	s_waitcnt lgkmcnt(0)
	v_pk_mul_f32 v[162:163], v[136:137], v[136:137]
	v_pk_mul_f32 v[160:161], v[138:139], v[138:139]
	v_add_f32_e32 v141, v162, v163
	v_add_f32_e32 v141, v160, v141
	v_add_f32_e32 v141, v161, v141
	s_nop 1
	v_readlane_b32 s16, v253, 6
	v_readlane_b32 s17, v253, 7
	s_waitcnt lgkmcnt(0)
	v_add_f32_dpp v141, v141, v141 quad_perm:[1,0,3,2] row_mask:0xf bank_mask:0xf
	s_nop 1
	s_waitcnt lgkmcnt(0)
	v_add_f32_dpp v141, v141, v141 quad_perm:[2,3,0,1] row_mask:0xf bank_mask:0xf
	s_nop 1
	s_waitcnt lgkmcnt(0)
	v_add_f32_dpp v141, v141, v141 row_half_mirror row_mask:0xf bank_mask:0xf
	s_nop 1
	s_waitcnt lgkmcnt(0)
	v_add_f32_dpp v141, v141, v141 row_mirror row_mask:0xf bank_mask:0xf
	v_mov_b32_e32 v159, v141
	s_nop 1
	v_permlane16_swap_b32_e32 v159, v141
	s_waitcnt lgkmcnt(0)
	v_add_f32_e32 v141, v141, v159
	v_fmamk_f32 v141, v141, 0x3c000000, v1
	v_cmp_gt_f32_e32 vcc, s29, v141
	v_mul_f32_e32 v159, 0x4b800000, v141
	s_nop 0
	v_cndmask_b32_e32 v141, v141, v159, vcc
	v_rsq_f32_e32 v141, v141
	s_nop 0
	v_mul_f32_e32 v159, 0x45800000, v141
	v_cndmask_b32_e32 v160, v141, v159, vcc
	v_pk_mul_f32 v[136:137], v[136:137], v[160:161] op_sel_hi:[1,0]
	v_pk_mul_f32 v[138:139], v[138:139], v[160:161] op_sel_hi:[1,0]
	v_pk_mul_f32 v[136:137], v[132:133], v[136:137]
	v_pk_mul_f32 v[138:139], v[134:135], v[138:139]
	s_and_b64 vcc, exec, s[38:39]
	s_cbranch_vccnz .LBB0_339
	v_add_u32_e32 v160, s6, v158
	v_readlane_b32 s0, v251, 28
	v_ashrrev_i32_e32 v161, 31, v160
	s_add_u32 s0, s0, s4
	v_readlane_b32 s1, v251, 29
	s_addc_u32 s1, s1, s5
	v_lshlrev_b64 v[160:161], 9, v[160:161]
	v_lshl_add_u64 v[160:161], s[0:1], 0, v[160:161]
	v_mov_b32_e32 v141, v3
	v_lshl_add_u64 v[160:161], v[160:161], 0, v[140:141]
	global_store_dwordx4 v[160:161], v[136:139], off
.LBB0_339:
	v_add_u32_e32 v158, s83, v158
	v_ashrrev_i32_e32 v159, 31, v158
	v_readlane_b32 s12, v253, 2
	v_lshlrev_b64 v[158:159], 8, v[158:159]
	v_readlane_b32 s18, v253, 8
	v_readlane_b32 s19, v253, 9
	v_cvt_pk_bf16_f32 v136, v136, v137
	v_cvt_pk_bf16_f32 v137, v138, v139
	v_lshl_add_u64 v[158:159], s[18:19], 0, v[158:159]
	v_lshl_add_u64 v[158:159], v[158:159], 0, v[2:3]
	global_store_dwordx2 v[158:159], v[136:137], off
	ds_read_b128 v[136:139], v157 offset:46464
	v_add_u32_e32 v158, 0x58, v142
	v_readlane_b32 s13, v253, 3
	v_readlane_b32 s14, v253, 4
	v_readlane_b32 s15, v253, 5
	s_waitcnt lgkmcnt(0)
	v_pk_mul_f32 v[162:163], v[136:137], v[136:137]
	v_pk_mul_f32 v[160:161], v[138:139], v[138:139]
	v_add_f32_e32 v141, v162, v163
	v_add_f32_e32 v141, v160, v141
	v_add_f32_e32 v141, v161, v141
	s_nop 1
	v_readlane_b32 s16, v253, 6
	v_readlane_b32 s17, v253, 7
	s_waitcnt lgkmcnt(0)
	v_add_f32_dpp v141, v141, v141 quad_perm:[1,0,3,2] row_mask:0xf bank_mask:0xf
	s_nop 1
	s_waitcnt lgkmcnt(0)
	v_add_f32_dpp v141, v141, v141 quad_perm:[2,3,0,1] row_mask:0xf bank_mask:0xf
	s_nop 1
	s_waitcnt lgkmcnt(0)
	v_add_f32_dpp v141, v141, v141 row_half_mirror row_mask:0xf bank_mask:0xf
	s_nop 1
	s_waitcnt lgkmcnt(0)
	v_add_f32_dpp v141, v141, v141 row_mirror row_mask:0xf bank_mask:0xf
	v_mov_b32_e32 v159, v141
	s_nop 1
	v_permlane16_swap_b32_e32 v159, v141
	s_waitcnt lgkmcnt(0)
	v_add_f32_e32 v141, v141, v159
	v_fmamk_f32 v141, v141, 0x3c000000, v1
	v_cmp_gt_f32_e32 vcc, s29, v141
	v_mul_f32_e32 v159, 0x4b800000, v141
	s_nop 0
	v_cndmask_b32_e32 v141, v141, v159, vcc
	v_rsq_f32_e32 v141, v141
	s_nop 0
	v_mul_f32_e32 v159, 0x45800000, v141
	v_cndmask_b32_e32 v160, v141, v159, vcc
	v_pk_mul_f32 v[136:137], v[136:137], v[160:161] op_sel_hi:[1,0]
	v_pk_mul_f32 v[138:139], v[138:139], v[160:161] op_sel_hi:[1,0]
	v_pk_mul_f32 v[136:137], v[132:133], v[136:137]
	v_pk_mul_f32 v[138:139], v[134:135], v[138:139]
	s_and_b64 vcc, exec, s[38:39]
	s_cbranch_vccnz .LBB0_341
	v_add_u32_e32 v160, s6, v158
	v_readlane_b32 s0, v251, 28
	v_ashrrev_i32_e32 v161, 31, v160
	s_add_u32 s0, s0, s4
	v_readlane_b32 s1, v251, 29
	s_addc_u32 s1, s1, s5
	v_lshlrev_b64 v[160:161], 9, v[160:161]
	v_lshl_add_u64 v[160:161], s[0:1], 0, v[160:161]
	v_mov_b32_e32 v141, v3
	v_lshl_add_u64 v[160:161], v[160:161], 0, v[140:141]
	global_store_dwordx4 v[160:161], v[136:139], off
.LBB0_341:
	v_add_u32_e32 v158, s83, v158
	v_ashrrev_i32_e32 v159, 31, v158
	v_readlane_b32 s12, v253, 2
	v_lshlrev_b64 v[158:159], 8, v[158:159]
	v_readlane_b32 s18, v253, 8
	v_readlane_b32 s19, v253, 9
	v_cvt_pk_bf16_f32 v136, v136, v137
	v_cvt_pk_bf16_f32 v137, v138, v139
	v_lshl_add_u64 v[158:159], s[18:19], 0, v[158:159]
	v_lshl_add_u64 v[158:159], v[158:159], 0, v[2:3]
	global_store_dwordx2 v[158:159], v[136:137], off
	ds_read_b128 v[136:139], v157 offset:50688
	v_add_u32_e32 v158, 0x60, v142
	v_readlane_b32 s13, v253, 3
	v_readlane_b32 s14, v253, 4
	v_readlane_b32 s15, v253, 5
	s_waitcnt lgkmcnt(0)
	v_pk_mul_f32 v[162:163], v[136:137], v[136:137]
	v_pk_mul_f32 v[160:161], v[138:139], v[138:139]
	v_add_f32_e32 v141, v162, v163
	v_add_f32_e32 v141, v160, v141
	v_add_f32_e32 v141, v161, v141
	s_nop 1
	v_readlane_b32 s16, v253, 6
	v_readlane_b32 s17, v253, 7
	s_waitcnt lgkmcnt(0)
	v_add_f32_dpp v141, v141, v141 quad_perm:[1,0,3,2] row_mask:0xf bank_mask:0xf
	s_nop 1
	s_waitcnt lgkmcnt(0)
	v_add_f32_dpp v141, v141, v141 quad_perm:[2,3,0,1] row_mask:0xf bank_mask:0xf
	s_nop 1
	s_waitcnt lgkmcnt(0)
	v_add_f32_dpp v141, v141, v141 row_half_mirror row_mask:0xf bank_mask:0xf
	s_nop 1
	s_waitcnt lgkmcnt(0)
	v_add_f32_dpp v141, v141, v141 row_mirror row_mask:0xf bank_mask:0xf
	v_mov_b32_e32 v159, v141
	s_nop 1
	v_permlane16_swap_b32_e32 v159, v141
	s_waitcnt lgkmcnt(0)
	v_add_f32_e32 v141, v141, v159
	v_fmamk_f32 v141, v141, 0x3c000000, v1
	v_cmp_gt_f32_e32 vcc, s29, v141
	v_mul_f32_e32 v159, 0x4b800000, v141
	s_nop 0
	v_cndmask_b32_e32 v141, v141, v159, vcc
	v_rsq_f32_e32 v141, v141
	s_nop 0
	v_mul_f32_e32 v159, 0x45800000, v141
	v_cndmask_b32_e32 v160, v141, v159, vcc
	v_pk_mul_f32 v[136:137], v[136:137], v[160:161] op_sel_hi:[1,0]
	v_pk_mul_f32 v[138:139], v[138:139], v[160:161] op_sel_hi:[1,0]
	v_pk_mul_f32 v[136:137], v[132:133], v[136:137]
	v_pk_mul_f32 v[138:139], v[134:135], v[138:139]
	s_and_b64 vcc, exec, s[38:39]
	s_cbranch_vccnz .LBB0_343
	v_add_u32_e32 v160, s6, v158
	v_readlane_b32 s0, v251, 28
	v_ashrrev_i32_e32 v161, 31, v160
	s_add_u32 s0, s0, s4
	v_readlane_b32 s1, v251, 29
	s_addc_u32 s1, s1, s5
	v_lshlrev_b64 v[160:161], 9, v[160:161]
	v_lshl_add_u64 v[160:161], s[0:1], 0, v[160:161]
	v_mov_b32_e32 v141, v3
	v_lshl_add_u64 v[160:161], v[160:161], 0, v[140:141]
	global_store_dwordx4 v[160:161], v[136:139], off
.LBB0_343:
	v_add_u32_e32 v158, s83, v158
	v_ashrrev_i32_e32 v159, 31, v158
	v_readlane_b32 s12, v253, 2
	v_lshlrev_b64 v[158:159], 8, v[158:159]
	v_readlane_b32 s18, v253, 8
	v_readlane_b32 s19, v253, 9
	v_cvt_pk_bf16_f32 v136, v136, v137
	v_cvt_pk_bf16_f32 v137, v138, v139
	v_lshl_add_u64 v[158:159], s[18:19], 0, v[158:159]
	v_lshl_add_u64 v[158:159], v[158:159], 0, v[2:3]
	global_store_dwordx2 v[158:159], v[136:137], off
	ds_read_b128 v[136:139], v157 offset:54912
	v_add_u32_e32 v158, 0x68, v142
	v_readlane_b32 s13, v253, 3
	v_readlane_b32 s14, v253, 4
	v_readlane_b32 s15, v253, 5
	s_waitcnt lgkmcnt(0)
	v_pk_mul_f32 v[162:163], v[136:137], v[136:137]
	v_pk_mul_f32 v[160:161], v[138:139], v[138:139]
	v_add_f32_e32 v141, v162, v163
	v_add_f32_e32 v141, v160, v141
	v_add_f32_e32 v141, v161, v141
	s_nop 1
	v_readlane_b32 s16, v253, 6
	v_readlane_b32 s17, v253, 7
	s_waitcnt lgkmcnt(0)
	v_add_f32_dpp v141, v141, v141 quad_perm:[1,0,3,2] row_mask:0xf bank_mask:0xf
	s_nop 1
	s_waitcnt lgkmcnt(0)
	v_add_f32_dpp v141, v141, v141 quad_perm:[2,3,0,1] row_mask:0xf bank_mask:0xf
	s_nop 1
	s_waitcnt lgkmcnt(0)
	v_add_f32_dpp v141, v141, v141 row_half_mirror row_mask:0xf bank_mask:0xf
	s_nop 1
	s_waitcnt lgkmcnt(0)
	v_add_f32_dpp v141, v141, v141 row_mirror row_mask:0xf bank_mask:0xf
	v_mov_b32_e32 v159, v141
	s_nop 1
	v_permlane16_swap_b32_e32 v159, v141
	s_waitcnt lgkmcnt(0)
	v_add_f32_e32 v141, v141, v159
	v_fmamk_f32 v141, v141, 0x3c000000, v1
	v_cmp_gt_f32_e32 vcc, s29, v141
	v_mul_f32_e32 v159, 0x4b800000, v141
	s_nop 0
	v_cndmask_b32_e32 v141, v141, v159, vcc
	v_rsq_f32_e32 v141, v141
	s_nop 0
	v_mul_f32_e32 v159, 0x45800000, v141
	v_cndmask_b32_e32 v160, v141, v159, vcc
	v_pk_mul_f32 v[136:137], v[136:137], v[160:161] op_sel_hi:[1,0]
	v_pk_mul_f32 v[138:139], v[138:139], v[160:161] op_sel_hi:[1,0]
	v_pk_mul_f32 v[136:137], v[132:133], v[136:137]
	v_pk_mul_f32 v[138:139], v[134:135], v[138:139]
	s_and_b64 vcc, exec, s[38:39]
	s_cbranch_vccnz .LBB0_345
	v_add_u32_e32 v160, s6, v158
	v_readlane_b32 s0, v251, 28
	v_ashrrev_i32_e32 v161, 31, v160
	s_add_u32 s0, s0, s4
	v_readlane_b32 s1, v251, 29
	s_addc_u32 s1, s1, s5
	v_lshlrev_b64 v[160:161], 9, v[160:161]
	v_lshl_add_u64 v[160:161], s[0:1], 0, v[160:161]
	v_mov_b32_e32 v141, v3
	v_lshl_add_u64 v[160:161], v[160:161], 0, v[140:141]
	global_store_dwordx4 v[160:161], v[136:139], off
.LBB0_345:
	v_add_u32_e32 v158, s83, v158
	v_ashrrev_i32_e32 v159, 31, v158
	v_readlane_b32 s12, v253, 2
	v_lshlrev_b64 v[158:159], 8, v[158:159]
	v_readlane_b32 s18, v253, 8
	v_readlane_b32 s19, v253, 9
	v_cvt_pk_bf16_f32 v136, v136, v137
	v_cvt_pk_bf16_f32 v137, v138, v139
	v_lshl_add_u64 v[158:159], s[18:19], 0, v[158:159]
	v_lshl_add_u64 v[158:159], v[158:159], 0, v[2:3]
	global_store_dwordx2 v[158:159], v[136:137], off
	ds_read_b128 v[136:139], v157 offset:59136
	v_add_u32_e32 v158, 0x70, v142
	v_readlane_b32 s13, v253, 3
	v_readlane_b32 s14, v253, 4
	v_readlane_b32 s15, v253, 5
	s_waitcnt lgkmcnt(0)
	v_pk_mul_f32 v[162:163], v[136:137], v[136:137]
	v_pk_mul_f32 v[160:161], v[138:139], v[138:139]
	v_add_f32_e32 v141, v162, v163
	v_add_f32_e32 v141, v160, v141
	v_add_f32_e32 v141, v161, v141
	s_nop 1
	v_readlane_b32 s16, v253, 6
	v_readlane_b32 s17, v253, 7
	s_waitcnt lgkmcnt(0)
	v_add_f32_dpp v141, v141, v141 quad_perm:[1,0,3,2] row_mask:0xf bank_mask:0xf
	s_nop 1
	s_waitcnt lgkmcnt(0)
	v_add_f32_dpp v141, v141, v141 quad_perm:[2,3,0,1] row_mask:0xf bank_mask:0xf
	s_nop 1
	s_waitcnt lgkmcnt(0)
	v_add_f32_dpp v141, v141, v141 row_half_mirror row_mask:0xf bank_mask:0xf
	s_nop 1
	s_waitcnt lgkmcnt(0)
	v_add_f32_dpp v141, v141, v141 row_mirror row_mask:0xf bank_mask:0xf
	v_mov_b32_e32 v159, v141
	s_nop 1
	v_permlane16_swap_b32_e32 v159, v141
	s_waitcnt lgkmcnt(0)
	v_add_f32_e32 v141, v141, v159
	v_fmamk_f32 v141, v141, 0x3c000000, v1
	v_cmp_gt_f32_e32 vcc, s29, v141
	v_mul_f32_e32 v159, 0x4b800000, v141
	s_nop 0
	v_cndmask_b32_e32 v141, v141, v159, vcc
	v_rsq_f32_e32 v141, v141
	s_nop 0
	v_mul_f32_e32 v159, 0x45800000, v141
	v_cndmask_b32_e32 v160, v141, v159, vcc
	v_pk_mul_f32 v[136:137], v[136:137], v[160:161] op_sel_hi:[1,0]
	v_pk_mul_f32 v[138:139], v[138:139], v[160:161] op_sel_hi:[1,0]
	v_pk_mul_f32 v[136:137], v[132:133], v[136:137]
	v_pk_mul_f32 v[138:139], v[134:135], v[138:139]
	s_and_b64 vcc, exec, s[38:39]
	s_cbranch_vccnz .LBB0_347
	v_add_u32_e32 v160, s6, v158
	v_readlane_b32 s0, v251, 28
	v_ashrrev_i32_e32 v161, 31, v160
	s_add_u32 s0, s0, s4
	v_readlane_b32 s1, v251, 29
	s_addc_u32 s1, s1, s5
	v_lshlrev_b64 v[160:161], 9, v[160:161]
	v_lshl_add_u64 v[160:161], s[0:1], 0, v[160:161]
	v_mov_b32_e32 v141, v3
	v_lshl_add_u64 v[160:161], v[160:161], 0, v[140:141]
	global_store_dwordx4 v[160:161], v[136:139], off
.LBB0_347:
	ds_read_b128 v[160:163], v157 offset:63360
	v_readlane_b32 s12, v253, 2
	v_cvt_pk_bf16_f32 v159, v138, v139
	v_readlane_b32 s18, v253, 8
	v_readlane_b32 s19, v253, 9
	s_waitcnt lgkmcnt(0)
	v_pk_mul_f32 v[166:167], v[160:161], v[160:161]
	v_pk_mul_f32 v[164:165], v[162:163], v[162:163]
	v_add_f32_e32 v141, v166, v167
	v_add_f32_e32 v141, v164, v141
	v_add_f32_e32 v141, v165, v141
	s_nop 1
	s_and_b64 vcc, exec, s[38:39]
	v_readlane_b32 s13, v253, 3
	v_readlane_b32 s14, v253, 4
	v_readlane_b32 s15, v253, 5
	s_waitcnt lgkmcnt(0)
	v_add_f32_dpp v141, v141, v141 quad_perm:[1,0,3,2] row_mask:0xf bank_mask:0xf
	s_nop 1
	v_add_u32_e32 v152, s83, v158
	v_cvt_pk_bf16_f32 v158, v136, v137
	v_add_u32_e32 v136, 0x78, v142
	v_readlane_b32 s16, v253, 6
	s_waitcnt lgkmcnt(0)
	v_add_f32_dpp v141, v141, v141 quad_perm:[2,3,0,1] row_mask:0xf bank_mask:0xf
	s_nop 1
	v_ashrrev_i32_e32 v153, 31, v152
	v_lshlrev_b64 v[138:139], 8, v[152:153]
	v_lshl_add_u64 v[138:139], s[18:19], 0, v[138:139]
	v_lshl_add_u64 v[138:139], v[138:139], 0, v[2:3]
	s_waitcnt lgkmcnt(0)
	v_add_f32_dpp v141, v141, v141 row_half_mirror row_mask:0xf bank_mask:0xf
	s_nop 1
	global_store_dwordx2 v[138:139], v[158:159], off
	v_readlane_b32 s17, v253, 7
	s_waitcnt lgkmcnt(0)
	v_add_f32_dpp v137, v141, v141 row_mirror row_mask:0xf bank_mask:0xf
	v_mov_b32_e32 v141, v137
	s_nop 1
	v_permlane16_swap_b32_e32 v141, v137
	s_waitcnt lgkmcnt(0)
	v_add_f32_e32 v137, v137, v141
	v_fmamk_f32 v137, v137, 0x3c000000, v1
	v_mul_f32_e32 v141, 0x4b800000, v137
	v_cmp_gt_f32_e64 s[0:1], s29, v137
	s_nop 1
	v_cndmask_b32_e64 v137, v137, v141, s[0:1]
	v_rsq_f32_e32 v137, v137
	s_nop 0
	v_mul_f32_e32 v138, 0x45800000, v137
	v_cndmask_b32_e64 v138, v137, v138, s[0:1]
	v_pk_mul_f32 v[142:143], v[160:161], v[138:139] op_sel_hi:[1,0]
	v_pk_mul_f32 v[138:139], v[162:163], v[138:139] op_sel_hi:[1,0]
	v_pk_mul_f32 v[132:133], v[132:133], v[142:143]
	v_pk_mul_f32 v[134:135], v[134:135], v[138:139]
	s_cbranch_vccnz .LBB0_349
	v_add_u32_e32 v138, s6, v136
	v_readlane_b32 s0, v251, 28
	v_ashrrev_i32_e32 v139, 31, v138
	s_add_u32 s0, s0, s4
	v_readlane_b32 s1, v251, 29
	s_addc_u32 s1, s1, s5
	v_lshlrev_b64 v[138:139], 9, v[138:139]
	v_lshl_add_u64 v[138:139], s[0:1], 0, v[138:139]
	v_mov_b32_e32 v141, v3
	v_lshl_add_u64 v[138:139], v[138:139], 0, v[140:141]
	global_store_dwordx4 v[138:139], v[132:135], off

.LBB0_356:
	v_mov_b32_e32 v136, 0
	v_mov_b32_e32 v137, 0
	v_mov_b32_e32 v138, 0
	v_mov_b32_e32 v139, 0
	s_and_saveexec_b64 s[36:37], s[0:1]
	v_add_u32_e32 v2, s38, v163
	ds_read_b128 v[136:139], v2
	s_or_b64 exec, exec, s[36:37]
	s_waitcnt lgkmcnt(0)
	v_pk_mul_f32 v[164:165], v[136:137], v[136:137]
	v_pk_mul_f32 v[154:155], v[138:139], v[138:139]
	v_add_f32_e32 v2, v164, v165
	v_add_f32_e32 v2, v154, v2
	v_add_f32_e32 v2, v155, v2
	s_nop 1
	s_waitcnt lgkmcnt(0)
	v_add_f32_dpp v2, v2, v2 quad_perm:[1,0,3,2] row_mask:0xf bank_mask:0xf
	s_nop 1
	s_waitcnt lgkmcnt(0)
	v_add_f32_dpp v2, v2, v2 quad_perm:[2,3,0,1] row_mask:0xf bank_mask:0xf
	s_nop 1
	s_waitcnt lgkmcnt(0)
	v_add_f32_dpp v2, v2, v2 row_half_mirror row_mask:0xf bank_mask:0xf
	s_nop 1
	s_waitcnt lgkmcnt(0)
	v_add_f32_dpp v2, v2, v2 row_mirror row_mask:0xf bank_mask:0xf
	v_mov_b32_e32 v154, v2
	s_nop 1
	v_permlane16_swap_b32_e32 v154, v2
	s_waitcnt lgkmcnt(0)
	v_add_f32_e32 v2, v2, v154
	v_fmamk_f32 v2, v2, 0x3c2aaaab, v1
	v_cmp_gt_f32_e32 vcc, s29, v2
	v_mul_f32_e32 v154, 0x4b800000, v2
	s_nop 0
	v_cndmask_b32_e32 v2, v2, v154, vcc
	v_rsq_f32_e32 v2, v2
	s_nop 0
	v_mul_f32_e32 v154, 0x45800000, v2
	v_cndmask_b32_e32 v2, v2, v154, vcc
	v_pk_mul_f32 v[136:137], v[136:137], v[2:3] op_sel_hi:[1,0]
	s_andn2_b64 vcc, exec, s[34:35]
	s_waitcnt vmcnt(0)
	v_pk_mul_f32 v[154:155], v[132:133], v[136:137]
	v_pk_mul_f32 v[136:137], v[138:139], v[2:3] op_sel_hi:[1,0]
	s_nop 0
	v_pk_mul_f32 v[136:137], v[134:135], v[136:137]
	s_cbranch_vccnz .LBB0_360
	v_add_u32_e32 v2, s86, v157
	v_ashrrev_i32_e32 v2, 6, v2
	v_and_b32_e32 v138, 63, v157
	v_cndmask_b32_e64 v2, v138, v2, s[8:9]
	v_lshlrev_b32_e32 v138, 3, v2
	v_ashrrev_i32_e32 v139, 31, v138
	v_lshlrev_b64 v[138:139], 2, v[138:139]
	v_lshl_add_u64 v[164:165], v[142:143], 0, v[138:139]
	global_load_dwordx4 v[164:167], v[164:165], off
	v_lshl_add_u64 v[138:139], v[140:141], 0, v[138:139]
	global_load_dwordx4 v[168:171], v[138:139], off
	ds_bpermute_b32 v2, v159, v155
	ds_bpermute_b32 v138, v159, v154
	ds_bpermute_b32 v176, v159, v136
	ds_bpermute_b32 v177, v159, v137
	s_waitcnt lgkmcnt(3)
	v_cndmask_b32_e64 v139, v2, -v2, s[4:5]
	s_waitcnt lgkmcnt(2)
	v_cndmask_b32_e64 v138, v138, -v138, s[4:5]
	s_waitcnt lgkmcnt(1)
	v_cndmask_b32_e64 v176, v176, -v176, s[4:5]
	s_waitcnt lgkmcnt(0)
	v_cndmask_b32_e64 v177, v177, -v177, s[4:5]
	s_waitcnt vmcnt(1)
	v_pk_mul_f32 v[166:167], v[166:167], v[176:177]
	v_pk_mul_f32 v[138:139], v[164:165], v[138:139]
	s_waitcnt vmcnt(0)
	v_pk_fma_f32 v[164:165], v[136:137], v[170:171], v[166:167]
	v_pk_fma_f32 v[138:139], v[154:155], v[168:169], v[138:139]
	v_cndmask_b32_e64 v136, v136, v164, s[6:7]
	v_cndmask_b32_e64 v137, v137, v165, s[6:7]
	v_cndmask_b32_e64 v154, v154, v138, s[6:7]
	v_cndmask_b32_e64 v155, v155, v139, s[6:7]

.LBB0_381:
	ds_read_b128 v[136:139], v181
	v_and_b32_e32 v182, 63, v176
	s_andn2_b64 vcc, exec, s[36:37]
	s_waitcnt lgkmcnt(0)
	v_pk_mul_f32 v[142:143], v[136:137], v[136:137]
	v_pk_mul_f32 v[140:141], v[138:139], v[138:139]
	v_add_f32_e32 v2, v142, v143
	v_add_f32_e32 v2, v140, v2
	v_add_f32_e32 v2, v141, v2
	s_nop 1
	v_add_u32_e32 v141, s86, v176
	v_ashrrev_i32_e32 v183, 6, v141
	s_waitcnt lgkmcnt(0)
	v_add_f32_dpp v2, v2, v2 quad_perm:[1,0,3,2] row_mask:0xf bank_mask:0xf
	s_nop 1
	s_waitcnt lgkmcnt(0)
	v_add_f32_dpp v2, v2, v2 quad_perm:[2,3,0,1] row_mask:0xf bank_mask:0xf
	s_nop 1
	s_waitcnt lgkmcnt(0)
	v_add_f32_dpp v2, v2, v2 row_half_mirror row_mask:0xf bank_mask:0xf
	s_nop 1
	s_waitcnt lgkmcnt(0)
	v_add_f32_dpp v2, v2, v2 row_mirror row_mask:0xf bank_mask:0xf
	v_fmamk_f32 v2, v2, 0x3c800000, v1
	v_mul_f32_e32 v140, 0x4b800000, v2
	v_cmp_gt_f32_e64 s[4:5], s29, v2
	s_nop 1
	v_cndmask_b32_e64 v2, v2, v140, s[4:5]
	v_rsq_f32_e32 v2, v2
	s_nop 0
	v_mul_f32_e32 v140, 0x45800000, v2
	v_cndmask_b32_e64 v2, v2, v140, s[4:5]
	s_mov_b64 s[4:5], -1
	s_cbranch_vccnz .LBB0_411
	s_mov_b64 s[66:67], -1
	s_mov_b64 s[62:63], 0
	s_cmp_lt_i32 s8, 3
	s_mov_b64 s[4:5], 0
	s_mov_b64 s[64:65], 0
	s_cbranch_scc1 .LBB0_388
	s_cmp_gt_i32 s8, 4
	s_cbranch_scc0 .LBB0_385
	s_cmp_lg_u32 s8, 5
	s_mov_b64 s[66:67], 0
	s_mov_b64 s[4:5], -1
	s_cselect_b64 s[64:65], -1, 0

.LBB0_429:
	s_or_b64 exec, exec, s[0:1]
	v_lshlrev_b32_e32 v172, 2, v133
	v_and_b32_e32 v133, 64, v190
	v_xor_b32_e32 v2, 1, v190
	v_add_u32_e32 v133, 64, v133
	v_cmp_lt_i32_e64 s[0:1], v2, v133
	s_waitcnt lgkmcnt(0)
	v_pk_mul_f32 v[134:135], v[142:143], v[142:143]
	s_waitcnt vmcnt(0)
	v_pk_mul_f32 v[144:145], v[136:137], v[136:137]
	v_cndmask_b32_e64 v2, v190, v2, s[0:1]
	v_lshlrev_b32_e32 v164, 2, v2
	v_xor_b32_e32 v2, 2, v190
	v_cmp_lt_i32_e64 s[0:1], v2, v133
	s_nop 1
	v_cndmask_b32_e64 v2, v190, v2, s[0:1]
	v_lshlrev_b32_e32 v165, 2, v2
	v_xor_b32_e32 v2, 4, v190
	v_cmp_lt_i32_e64 s[0:1], v2, v133
	s_nop 1
	v_cndmask_b32_e64 v2, v190, v2, s[0:1]
	v_lshlrev_b32_e32 v166, 2, v2
	v_xor_b32_e32 v2, 8, v190
	v_cmp_lt_i32_e64 s[0:1], v2, v133
	v_mul_f32_e32 v133, v141, v141
	v_fmac_f32_e32 v133, v140, v140
	v_add_f32_e32 v133, v134, v133
	v_cndmask_b32_e64 v2, v190, v2, s[0:1]
	v_add_f32_e32 v133, v135, v133
	v_lshlrev_b32_e32 v167, 2, v2
	v_lshlrev_b32_e32 v2, 2, v172
	v_add_f32_e32 v133, v133, v144
	v_add_f32_e32 v133, v145, v133
	global_load_dwordx4 v[144:147], v2, s[30:31]
	v_pk_mul_f32 v[134:135], v[138:139], v[138:139]
	v_lshl_add_u64 v[152:153], s[30:31], 0, v[2:3]
	v_add_f32_e32 v133, v134, v133
	v_add_f32_e32 v133, v135, v133
	s_nop 1
	v_mov_b32_e32 v135, 0
	s_waitcnt lgkmcnt(0)
	v_add_f32_dpp v133, v133, v133 quad_perm:[1,0,3,2] row_mask:0xf bank_mask:0xf
	s_nop 1
	s_waitcnt lgkmcnt(0)
	v_add_f32_dpp v133, v133, v133 quad_perm:[2,3,0,1] row_mask:0xf bank_mask:0xf
	s_nop 1
	s_waitcnt lgkmcnt(0)
	v_add_f32_dpp v158, v133, v133 row_half_mirror row_mask:0xf bank_mask:0xf
	ds_bpermute_b32 v159, v167, v158
	v_mov_b32_e32 v133, 0
	v_mov_b32_e32 v134, 0
	s_and_saveexec_b64 s[0:1], vcc
	s_cbranch_execz .LBB0_431
	global_load_dwordx4 v[132:135], v[152:153], off offset:256

.LBB0_435:
	s_or_b64 exec, exec, s[0:1]
	s_waitcnt lgkmcnt(0)
	v_mul_f32_e32 v133, v141, v141
	v_fmac_f32_e32 v133, v140, v140
	v_pk_mul_f32 v[134:135], v[142:143], v[142:143]
	s_waitcnt vmcnt(0)
	v_pk_mul_f32 v[144:145], v[136:137], v[136:137]
	v_add_f32_e32 v133, v134, v133
	v_add_f32_e32 v133, v135, v133
	v_add_f32_e32 v133, v133, v144
	v_add_f32_e32 v133, v145, v133
	global_load_dwordx4 v[144:147], v[152:153], off
	v_pk_mul_f32 v[134:135], v[138:139], v[138:139]
	s_nop 0
	v_add_f32_e32 v133, v134, v133
	v_add_f32_e32 v133, v135, v133
	s_nop 1
	v_mov_b32_e32 v135, 0
	s_waitcnt lgkmcnt(0)
	v_add_f32_dpp v133, v133, v133 quad_perm:[1,0,3,2] row_mask:0xf bank_mask:0xf
	s_nop 1
	s_waitcnt lgkmcnt(0)
	v_add_f32_dpp v133, v133, v133 quad_perm:[2,3,0,1] row_mask:0xf bank_mask:0xf
	s_nop 1
	s_waitcnt lgkmcnt(0)
	v_add_f32_dpp v162, v133, v133 row_half_mirror row_mask:0xf bank_mask:0xf
	ds_bpermute_b32 v163, v167, v162
	v_mov_b32_e32 v133, 0
	v_mov_b32_e32 v134, 0
	s_and_saveexec_b64 s[0:1], vcc
	s_cbranch_execz .LBB0_437
	global_load_dwordx4 v[132:135], v[152:153], off offset:256

.LBB0_441:
	s_or_b64 exec, exec, s[0:1]
	s_waitcnt lgkmcnt(0)
	v_mul_f32_e32 v133, v141, v141
	v_fmac_f32_e32 v133, v140, v140
	v_pk_mul_f32 v[134:135], v[142:143], v[142:143]
	s_waitcnt vmcnt(0)
	v_pk_mul_f32 v[144:145], v[136:137], v[136:137]
	v_add_f32_e32 v133, v134, v133
	v_add_f32_e32 v133, v135, v133
	v_add_f32_e32 v133, v133, v144
	v_add_f32_e32 v133, v145, v133
	global_load_dwordx4 v[144:147], v[152:153], off
	v_pk_mul_f32 v[134:135], v[138:139], v[138:139]
	s_nop 0
	v_add_f32_e32 v133, v134, v133
	v_add_f32_e32 v133, v135, v133
	s_nop 1
	v_mov_b32_e32 v135, 0
	s_waitcnt lgkmcnt(0)
	v_add_f32_dpp v133, v133, v133 quad_perm:[1,0,3,2] row_mask:0xf bank_mask:0xf
	s_nop 1
	s_waitcnt lgkmcnt(0)
	v_add_f32_dpp v133, v133, v133 quad_perm:[2,3,0,1] row_mask:0xf bank_mask:0xf
	s_nop 1
	s_waitcnt lgkmcnt(0)
	v_add_f32_dpp v160, v133, v133 row_half_mirror row_mask:0xf bank_mask:0xf
	ds_bpermute_b32 v161, v167, v160
	v_mov_b32_e32 v133, 0
	v_mov_b32_e32 v134, 0
	s_and_saveexec_b64 s[0:1], vcc
	s_cbranch_execz .LBB0_443
	global_load_dwordx4 v[132:135], v[152:153], off offset:256

.LBB0_455:
	s_or_b64 exec, exec, s[0:1]
	s_waitcnt lgkmcnt(0)
	v_mul_f32_e32 v5, v13, v13
	v_fmac_f32_e32 v5, v12, v12
	v_pk_mul_f32 v[6:7], v[14:15], v[14:15]
	s_waitcnt vmcnt(0)
	v_pk_mul_f32 v[16:17], v[8:9], v[8:9]
	v_add_f32_e32 v5, v6, v5
	v_add_f32_e32 v5, v7, v5
	v_add_f32_e32 v5, v5, v16
	v_add_f32_e32 v5, v17, v5
	global_load_dwordx4 v[16:19], v[152:153], off
	v_pk_mul_f32 v[6:7], v[10:11], v[10:11]
	s_nop 0
	v_add_f32_e32 v5, v6, v5
	v_add_f32_e32 v5, v7, v5
	s_nop 1
	v_mov_b32_e32 v7, 0
	s_waitcnt lgkmcnt(0)
	v_add_f32_dpp v5, v5, v5 quad_perm:[1,0,3,2] row_mask:0xf bank_mask:0xf
	s_nop 1
	s_waitcnt lgkmcnt(0)
	v_add_f32_dpp v5, v5, v5 quad_perm:[2,3,0,1] row_mask:0xf bank_mask:0xf
	s_nop 1
	s_waitcnt lgkmcnt(0)
	v_add_f32_dpp v22, v5, v5 row_half_mirror row_mask:0xf bank_mask:0xf
	ds_bpermute_b32 v23, v167, v22
	v_mov_b32_e32 v5, 0
	v_mov_b32_e32 v6, 0
	s_and_saveexec_b64 s[0:1], vcc
	s_cbranch_execz .LBB0_457
	global_load_dwordx4 v[4:7], v[152:153], off offset:256

.LBB0_498:
	s_or_b64 exec, exec, s[2:3]
	v_lshlrev_b32_e32 v176, 2, v137
	v_and_b32_e32 v137, 64, v190
	v_xor_b32_e32 v2, 1, v190
	v_add_u32_e32 v137, 64, v137
	v_cmp_lt_i32_e32 vcc, v2, v137
	s_waitcnt lgkmcnt(0)
	v_pk_mul_f32 v[138:139], v[134:135], v[134:135]
	s_waitcnt vmcnt(0)
	v_pk_mul_f32 v[144:145], v[140:141], v[140:141]
	v_cndmask_b32_e32 v2, v190, v2, vcc
	v_lshlrev_b32_e32 v169, 2, v2
	v_xor_b32_e32 v2, 2, v190
	v_cmp_lt_i32_e32 vcc, v2, v137
	s_nop 1
	v_cndmask_b32_e32 v2, v190, v2, vcc
	v_lshlrev_b32_e32 v168, 2, v2
	v_xor_b32_e32 v2, 4, v190
	v_cmp_lt_i32_e32 vcc, v2, v137
	s_nop 1
	v_cndmask_b32_e32 v2, v190, v2, vcc
	v_lshlrev_b32_e32 v170, 2, v2
	v_xor_b32_e32 v2, 8, v190
	v_cmp_lt_i32_e32 vcc, v2, v137
	v_mul_f32_e32 v137, v133, v133
	v_fmac_f32_e32 v137, v132, v132
	v_add_f32_e32 v137, v138, v137
	v_cndmask_b32_e32 v2, v190, v2, vcc
	v_add_f32_e32 v137, v139, v137
	v_lshlrev_b32_e32 v171, 2, v2
	v_lshlrev_b32_e32 v2, 2, v176
	v_add_f32_e32 v137, v137, v144
	v_add_f32_e32 v137, v145, v137
	global_load_dwordx4 v[144:147], v2, s[30:31]
	v_pk_mul_f32 v[138:139], v[142:143], v[142:143]
	v_lshl_add_u64 v[152:153], s[30:31], 0, v[2:3]
	v_add_f32_e32 v137, v138, v137
	v_add_f32_e32 v137, v139, v137
	s_nop 1
	v_mov_b32_e32 v139, 0
	s_waitcnt lgkmcnt(0)
	v_add_f32_dpp v137, v137, v137 quad_perm:[1,0,3,2] row_mask:0xf bank_mask:0xf
	s_nop 1
	s_waitcnt lgkmcnt(0)
	v_add_f32_dpp v137, v137, v137 quad_perm:[2,3,0,1] row_mask:0xf bank_mask:0xf
	s_nop 1
	s_waitcnt lgkmcnt(0)
	v_add_f32_dpp v158, v137, v137 row_half_mirror row_mask:0xf bank_mask:0xf
	ds_bpermute_b32 v159, v171, v158
	v_mov_b32_e32 v137, 0
	v_mov_b32_e32 v138, 0
	s_and_saveexec_b64 s[2:3], s[38:39]
	s_cbranch_execz .LBB0_500
	global_load_dwordx4 v[136:139], v[152:153], off offset:256

.LBB0_506:
	s_or_b64 exec, exec, s[0:1]
	s_waitcnt lgkmcnt(0)
	v_mul_f32_e32 v137, v133, v133
	v_fmac_f32_e32 v137, v132, v132
	v_pk_mul_f32 v[138:139], v[134:135], v[134:135]
	s_waitcnt vmcnt(0)
	v_pk_mul_f32 v[144:145], v[140:141], v[140:141]
	v_add_f32_e32 v137, v138, v137
	v_add_f32_e32 v137, v139, v137
	v_add_f32_e32 v137, v137, v144
	v_add_f32_e32 v137, v145, v137
	global_load_dwordx4 v[144:147], v[152:153], off
	v_pk_mul_f32 v[138:139], v[142:143], v[142:143]
	s_nop 0
	v_add_f32_e32 v137, v138, v137
	v_add_f32_e32 v137, v139, v137
	s_nop 1
	v_mov_b32_e32 v139, 0
	s_waitcnt lgkmcnt(0)
	v_add_f32_dpp v137, v137, v137 quad_perm:[1,0,3,2] row_mask:0xf bank_mask:0xf
	s_nop 1
	s_waitcnt lgkmcnt(0)
	v_add_f32_dpp v137, v137, v137 quad_perm:[2,3,0,1] row_mask:0xf bank_mask:0xf
	s_nop 1
	s_waitcnt lgkmcnt(0)
	v_add_f32_dpp v166, v137, v137 row_half_mirror row_mask:0xf bank_mask:0xf
	ds_bpermute_b32 v167, v171, v166
	v_mov_b32_e32 v137, 0
	v_mov_b32_e32 v138, 0
	s_and_saveexec_b64 s[0:1], s[38:39]
	s_movk_i32 s36, 0x1fff
	s_cbranch_execz .LBB0_508
	global_load_dwordx4 v[136:139], v[152:153], off offset:256

.LBB0_514:
	s_or_b64 exec, exec, s[4:5]
	s_waitcnt lgkmcnt(0)
	v_mul_f32_e32 v137, v133, v133
	v_fmac_f32_e32 v137, v132, v132
	v_pk_mul_f32 v[138:139], v[134:135], v[134:135]
	s_waitcnt vmcnt(0)
	v_pk_mul_f32 v[144:145], v[140:141], v[140:141]
	v_add_f32_e32 v137, v138, v137
	v_add_f32_e32 v137, v139, v137
	v_add_f32_e32 v137, v137, v144
	v_add_f32_e32 v137, v145, v137
	global_load_dwordx4 v[144:147], v[152:153], off
	v_pk_mul_f32 v[138:139], v[142:143], v[142:143]
	s_nop 0
	v_add_f32_e32 v137, v138, v137
	v_add_f32_e32 v137, v139, v137
	s_nop 1
	v_mov_b32_e32 v139, 0
	s_waitcnt lgkmcnt(0)
	v_add_f32_dpp v137, v137, v137 quad_perm:[1,0,3,2] row_mask:0xf bank_mask:0xf
	s_nop 1
	s_waitcnt lgkmcnt(0)
	v_add_f32_dpp v137, v137, v137 quad_perm:[2,3,0,1] row_mask:0xf bank_mask:0xf
	s_nop 1
	s_waitcnt lgkmcnt(0)
	v_add_f32_dpp v164, v137, v137 row_half_mirror row_mask:0xf bank_mask:0xf
	ds_bpermute_b32 v165, v171, v164
	v_mov_b32_e32 v137, 0
	v_mov_b32_e32 v138, 0
	s_and_saveexec_b64 s[4:5], s[38:39]
	s_cbranch_execz .LBB0_516
	global_load_dwordx4 v[136:139], v[152:153], off offset:256

.LBB0_522:
	s_or_b64 exec, exec, s[4:5]
	s_waitcnt lgkmcnt(0)
	v_mul_f32_e32 v137, v133, v133
	v_fmac_f32_e32 v137, v132, v132
	v_pk_mul_f32 v[138:139], v[134:135], v[134:135]
	s_waitcnt vmcnt(0)
	v_pk_mul_f32 v[144:145], v[140:141], v[140:141]
	v_add_f32_e32 v137, v138, v137
	v_add_f32_e32 v137, v139, v137
	v_add_f32_e32 v137, v137, v144
	v_add_f32_e32 v137, v145, v137
	global_load_dwordx4 v[144:147], v[152:153], off
	v_pk_mul_f32 v[138:139], v[142:143], v[142:143]
	s_nop 0
	v_add_f32_e32 v137, v138, v137
	v_add_f32_e32 v137, v139, v137
	s_nop 1
	v_mov_b32_e32 v139, 0
	s_waitcnt lgkmcnt(0)
	v_add_f32_dpp v137, v137, v137 quad_perm:[1,0,3,2] row_mask:0xf bank_mask:0xf
	s_nop 1
	s_waitcnt lgkmcnt(0)
	v_add_f32_dpp v137, v137, v137 quad_perm:[2,3,0,1] row_mask:0xf bank_mask:0xf
	s_nop 1
	s_waitcnt lgkmcnt(0)
	v_add_f32_dpp v166, v137, v137 row_half_mirror row_mask:0xf bank_mask:0xf
	ds_bpermute_b32 v167, v171, v166
	v_mov_b32_e32 v137, 0
	v_mov_b32_e32 v138, 0
	s_and_saveexec_b64 s[4:5], s[38:39]
	s_cbranch_execz .LBB0_524
	global_load_dwordx4 v[136:139], v[152:153], off offset:256

.LBB0_532:
	s_or_b64 exec, exec, s[4:5]
	s_waitcnt lgkmcnt(0)
	v_mul_f32_e32 v9, v5, v5
	v_fmac_f32_e32 v9, v4, v4
	v_pk_mul_f32 v[10:11], v[6:7], v[6:7]
	s_waitcnt vmcnt(0)
	v_pk_mul_f32 v[16:17], v[12:13], v[12:13]
	v_add_f32_e32 v9, v10, v9
	v_add_f32_e32 v9, v11, v9
	v_add_f32_e32 v9, v9, v16
	v_add_f32_e32 v9, v17, v9
	global_load_dwordx4 v[16:19], v[152:153], off
	v_pk_mul_f32 v[10:11], v[14:15], v[14:15]
	s_nop 0
	v_add_f32_e32 v9, v10, v9
	v_add_f32_e32 v9, v11, v9
	s_nop 1
	v_mov_b32_e32 v11, 0
	s_waitcnt lgkmcnt(0)
	v_add_f32_dpp v9, v9, v9 quad_perm:[1,0,3,2] row_mask:0xf bank_mask:0xf
	s_nop 1
	s_waitcnt lgkmcnt(0)
	v_add_f32_dpp v9, v9, v9 quad_perm:[2,3,0,1] row_mask:0xf bank_mask:0xf
	s_nop 1
	s_waitcnt lgkmcnt(0)
	v_add_f32_dpp v22, v9, v9 row_half_mirror row_mask:0xf bank_mask:0xf
	ds_bpermute_b32 v23, v171, v22
	v_mov_b32_e32 v9, 0
	v_mov_b32_e32 v10, 0
	s_and_saveexec_b64 s[4:5], s[38:39]
	s_cbranch_execz .LBB0_534
	global_load_dwordx4 v[8:11], v[152:153], off offset:256

.LBB0_594:
	v_ashrrev_i32_e32 v22, 11, v22
	v_add_u32_e32 v22, 1, v22
	v_cndmask_b32_e64 v22, v22, 0, s[0:1]
	v_readlane_b32 s16, v251, 7
	v_ashrrev_i32_e32 v23, 31, v22
	v_readlane_b32 s18, v251, 9
	v_readlane_b32 s19, v251, 10
	v_lshl_add_u64 v[22:23], v[22:23], 0, s[8:9]
	v_lshl_add_u64 v[20:21], v[20:21], 0, v[2:3]
	v_mov_b64_e32 v[24:25], s[18:19]
	v_mad_u64_u32 v[50:51], s[0:1], v22, s80, v[24:25]
	v_mad_i32_i24 v51, v23, s80, v51
	global_load_dwordx4 v[42:45], v[20:21], off
	global_load_dwordx4 v[46:49], v[20:21], off offset:1024
	global_load_dwordx4 v[24:27], v[20:21], off offset:2048
	s_nop 0
	global_load_dwordx4 v[20:23], v[20:21], off offset:3072
	s_waitcnt vmcnt(19)
	v_lshl_add_u64 v[78:79], v[50:51], 0, v[2:3]
	s_movk_i32 s5, 0x1000
	s_mov_b64 s[0:1], 0x1000
	v_add_co_u32_e32 v50, vcc, s5, v78
	v_lshl_add_u64 v[74:75], v[78:79], 0, s[0:1]
	s_nop 0
	v_addc_co_u32_e32 v51, vcc, 0, v79, vcc
	global_load_dwordx4 v[50:53], v[50:51], off
	s_nop 0
	global_load_dwordx4 v[54:57], v[78:79], off
	global_load_dwordx4 v[58:61], v[74:75], off offset:1024
	global_load_dwordx4 v[62:65], v[78:79], off offset:1024
	global_load_dwordx4 v[66:69], v[74:75], off offset:2048
	global_load_dwordx4 v[70:73], v[78:79], off offset:2048
	s_nop 0
	global_load_dwordx4 v[74:77], v[74:75], off offset:3072
	s_nop 0
	global_load_dwordx4 v[78:81], v[78:79], off offset:3072
	v_lshlrev_b64 v[34:35], 11, v[34:35]
	v_lshl_add_u64 v[34:35], v[30:31], 0, v[34:35]
	v_lshl_add_u64 v[28:29], v[28:29], 0, s[6:7]
	v_lshl_add_u64 v[32:33], v[32:33], 0, s[12:13]
	v_readlane_b32 s17, v251, 8
	s_waitcnt vmcnt(11)
	v_mov_b32_e32 v84, v43
	s_waitcnt vmcnt(10)
	v_mov_b32_e32 v85, v47
	v_mov_b32_e32 v82, v42
	v_mov_b32_e32 v83, v46
	v_pk_mul_f32 v[84:85], v[84:85], v[84:85]
	s_waitcnt vmcnt(9)
	v_mov_b32_e32 v86, v25
	v_pk_fma_f32 v[82:83], v[82:83], v[82:83], v[84:85]
	v_mov_b32_e32 v84, v44
	v_mov_b32_e32 v85, v48
	v_pk_fma_f32 v[82:83], v[84:85], v[84:85], v[82:83]
	v_mov_b32_e32 v84, v45
	v_mov_b32_e32 v85, v49
	s_waitcnt vmcnt(8)
	v_mov_b32_e32 v87, v21
	v_pk_fma_f32 v[82:83], v[84:85], v[84:85], v[82:83]
	v_mov_b32_e32 v84, v24
	v_mov_b32_e32 v85, v20
	v_pk_mul_f32 v[86:87], v[86:87], v[86:87]
	v_add_f32_e32 v82, v82, v83
	v_pk_fma_f32 v[84:85], v[84:85], v[84:85], v[86:87]
	v_mov_b32_e32 v86, v26
	v_mov_b32_e32 v87, v22
	v_pk_fma_f32 v[84:85], v[86:87], v[86:87], v[84:85]
	v_mov_b32_e32 v86, v27
	v_mov_b32_e32 v87, v23
	v_pk_fma_f32 v[84:85], v[86:87], v[86:87], v[84:85]
	s_waitcnt vmcnt(7)
	v_pk_add_f32 v[50:51], v[50:51], 1.0 op_sel_hi:[1,0]
	v_add_f32_e32 v82, v82, v84
	v_add_f32_e32 v82, v82, v85
	s_nop 1
	v_pk_mul_f32 v[50:51], v[16:17], v[50:51]
	s_waitcnt lgkmcnt(0)
	v_add_f32_dpp v82, v82, v82 quad_perm:[1,0,3,2] row_mask:0xf bank_mask:0xf
	s_nop 1
	s_waitcnt lgkmcnt(0)
	v_add_f32_dpp v82, v82, v82 quad_perm:[2,3,0,1] row_mask:0xf bank_mask:0xf
	s_nop 1
	s_waitcnt lgkmcnt(0)
	v_add_f32_dpp v82, v82, v82 row_half_mirror row_mask:0xf bank_mask:0xf
	s_nop 1
	s_waitcnt lgkmcnt(0)
	v_add_f32_dpp v82, v82, v82 row_mirror row_mask:0xf bank_mask:0xf
	v_mov_b32_e32 v83, v82
	s_nop 1
	v_permlane16_swap_b32_e32 v83, v82
	s_waitcnt lgkmcnt(0)
	v_add_f32_e32 v82, v82, v83
	v_mov_b32_e32 v83, v82
	s_nop 1
	v_permlane32_swap_b32_e32 v83, v82
	s_waitcnt lgkmcnt(0)
	v_add_f32_e32 v82, v82, v83
	v_fmamk_f32 v82, v82, 0x3a800000, v1
	v_cmp_gt_f32_e32 vcc, s86, v82
	v_mul_f32_e32 v83, 0x4b800000, v82
	s_nop 0
	v_cndmask_b32_e32 v82, v82, v83, vcc
	v_rsq_f32_e32 v82, v82
	s_nop 0
	v_mul_f32_e32 v83, 0x45800000, v82
	v_cndmask_b32_e32 v82, v82, v83, vcc
	v_pk_mul_f32 v[42:43], v[42:43], v[82:83] op_sel_hi:[1,0]
	v_pk_mul_f32 v[44:45], v[44:45], v[82:83] op_sel_hi:[1,0]
	s_waitcnt vmcnt(6)
	v_pk_fma_f32 v[42:43], v[50:51], v[42:43], v[54:55]
	v_pk_add_f32 v[50:51], v[52:53], 1.0 op_sel_hi:[1,0]
	v_cvt_pk_bf16_f32 v42, v42, v43
	v_pk_mul_f32 v[50:51], v[18:19], v[50:51]
	v_pk_mul_f32 v[24:25], v[24:25], v[82:83] op_sel_hi:[1,0]
	v_pk_fma_f32 v[44:45], v[50:51], v[44:45], v[56:57]
	v_pk_mul_f32 v[26:27], v[26:27], v[82:83] op_sel_hi:[1,0]
	v_cvt_pk_bf16_f32 v43, v44, v45
	s_waitcnt vmcnt(5)
	v_pk_add_f32 v[44:45], v[58:59], 1.0 op_sel_hi:[1,0]
	global_store_dwordx2 v[34:35], v[42:43], off
	v_pk_mul_f32 v[42:43], v[46:47], v[82:83] op_sel_hi:[1,0]
	v_pk_mul_f32 v[44:45], v[12:13], v[44:45]
	v_pk_add_f32 v[46:47], v[60:61], 1.0 op_sel_hi:[1,0]
	s_waitcnt vmcnt(5)
	v_pk_fma_f32 v[42:43], v[44:45], v[42:43], v[62:63]
	v_pk_mul_f32 v[44:45], v[48:49], v[82:83] op_sel_hi:[1,0]
	v_pk_mul_f32 v[46:47], v[14:15], v[46:47]
	v_cvt_pk_bf16_f32 v42, v42, v43
	v_pk_fma_f32 v[44:45], v[46:47], v[44:45], v[64:65]
	v_pk_mul_f32 v[20:21], v[20:21], v[82:83] op_sel_hi:[1,0]
	v_cvt_pk_bf16_f32 v43, v44, v45
	global_store_dwordx2 v[34:35], v[42:43], off offset:512
	s_waitcnt vmcnt(5)
	v_pk_add_f32 v[42:43], v[66:67], 1.0 op_sel_hi:[1,0]
	v_pk_mul_f32 v[22:23], v[22:23], v[82:83] op_sel_hi:[1,0]
	v_pk_mul_f32 v[42:43], v[8:9], v[42:43]
	v_cmp_lt_i32_e32 vcc, s36, v28
	s_waitcnt vmcnt(4)
	v_pk_fma_f32 v[24:25], v[42:43], v[24:25], v[70:71]
	v_pk_add_f32 v[42:43], v[68:69], 1.0 op_sel_hi:[1,0]
	v_cvt_pk_bf16_f32 v24, v24, v25
	v_pk_mul_f32 v[42:43], v[10:11], v[42:43]
	s_or_b64 s[14:15], vcc, s[14:15]
	v_pk_fma_f32 v[26:27], v[42:43], v[26:27], v[72:73]
	s_nop 0
	v_cvt_pk_bf16_f32 v25, v26, v27
	global_store_dwordx2 v[34:35], v[24:25], off offset:1024
	s_waitcnt vmcnt(4)
	v_pk_add_f32 v[24:25], v[74:75], 1.0 op_sel_hi:[1,0]
	s_nop 0
	v_pk_mul_f32 v[24:25], v[4:5], v[24:25]
	s_waitcnt vmcnt(3)
	v_pk_fma_f32 v[20:21], v[24:25], v[20:21], v[78:79]
	v_pk_add_f32 v[24:25], v[76:77], 1.0 op_sel_hi:[1,0]
	v_cvt_pk_bf16_f32 v20, v20, v21
	v_pk_mul_f32 v[24:25], v[6:7], v[24:25]
	s_nop 0
	v_pk_fma_f32 v[22:23], v[24:25], v[22:23], v[80:81]
	s_nop 0
	v_cvt_pk_bf16_f32 v21, v22, v23
	global_store_dwordx2 v[34:35], v[20:21], off offset:1536
	s_andn2_b64 exec, exec, s[14:15]
	s_cbranch_execz .LBB0_600
